# stack11 with the gate/up epilogue (ACT) stores marked sc1 nt (streaming write-through) instead of sc1
# baseline (speedup 1.0000x reference)
.LBB0_140:
	s_lshl_b32 s19, s67, 11
	s_add_i32 s19, s19, 0
	s_add_i32 s21, s19, 0x20180
	s_lshl_b32 s19, s45, 2
	s_add_i32 s19, s21, s19
	v_lshl_add_u32 v154, v165, 2, s19
	ds_read_b128 v[146:149], v154 offset:1024
	ds_read_b128 v[150:153], v154 offset:1536
	ds_read_b128 v[182:185], v154 offset:1040
	ds_read_b128 v[186:189], v154 offset:1552
	v_cvt_f32_i32_e32 v127, v127
	v_cvt_f32_i32_e32 v126, v126
	s_waitcnt lgkmcnt(0)
	v_pk_mul_f32 v[154:155], v[148:149], v[152:153]
	v_pk_mul_f32 v[158:159], v[146:147], v[150:151]
	v_pk_mul_f32 v[152:153], v[182:183], s[16:17] op_sel_hi:[1,0]
	v_pk_mul_f32 v[150:151], v[182:183], v[186:187]
	v_lshl_add_u32 v182, v167, 2, s21
	ds_read_b32 v186, v182
	v_cvt_f32_i32_e32 v123, v123
	v_cvt_f32_i32_e32 v122, v122
	v_pk_mul_f32 v[160:161], v[146:147], s[16:17] op_sel_hi:[1,0]
	v_cvt_f32_i32_e32 v129, v129
	v_cvt_f32_i32_e32 v128, v128
	s_waitcnt lgkmcnt(0)
	v_pk_mul_f32 v[190:191], v[160:161], v[186:187] op_sel_hi:[1,0]
	v_mul_f32_e32 v192, v186, v186
	v_pk_mul_f32 v[156:157], v[148:149], s[16:17] op_sel_hi:[1,0]
	v_pk_mul_f32 v[190:191], v[190:191], v[126:127]
	v_pk_mul_f32 v[122:123], v[126:127], v[122:123]
	v_pk_mul_f32 v[126:127], v[158:159], v[192:193] op_sel_hi:[1,0]
	v_cvt_f32_i32_e32 v125, v125
	v_pk_mul_f32 v[122:123], v[122:123], v[126:127]
	v_pk_mul_f32 v[126:127], v[156:157], v[186:187] op_sel_hi:[1,0]
	v_cvt_f32_i32_e32 v124, v124
	v_pk_mul_f32 v[126:127], v[126:127], v[128:129]
	v_exp_f32_e32 v190, v190
	v_exp_f32_e32 v126, v126
	v_exp_f32_e32 v127, v127
	v_exp_f32_e32 v191, v191
	v_cvt_f32_i32_e32 v119, v119
	v_cvt_f32_i32_e32 v118, v118
	v_pk_add_f32 v[126:127], v[126:127], 1.0 op_sel_hi:[1,0]
	v_pk_mul_f32 v[124:125], v[128:129], v[124:125]
	v_rcp_f32_e32 v126, v126
	v_rcp_f32_e32 v127, v127
	v_pk_mul_f32 v[128:129], v[154:155], v[192:193] op_sel_hi:[1,0]
	v_pk_add_f32 v[190:191], v[190:191], 1.0 op_sel_hi:[1,0]
	v_pk_mul_f32 v[124:125], v[124:125], v[128:129]
	v_rcp_f32_e32 v190, v190
	v_pk_mul_f32 v[124:125], v[124:125], v[126:127]
	v_pk_mul_f32 v[126:127], v[152:153], v[186:187] op_sel_hi:[1,0]
	v_rcp_f32_e32 v191, v191
	v_pk_mul_f32 v[126:127], v[126:127], v[118:119]
	v_cvt_f32_i32_e32 v115, v115
	v_exp_f32_e32 v126, v126
	v_exp_f32_e32 v127, v127
	v_cvt_f32_i32_e32 v114, v114
	v_cvt_f32_i32_e32 v121, v121
	v_cvt_f32_i32_e32 v120, v120
	v_pk_mul_f32 v[122:123], v[122:123], v[190:191]
	v_pk_mul_f32 v[148:149], v[184:185], s[16:17] op_sel_hi:[1,0]
	v_cvt_pk_bf16_f32 v122, v122, v123
	v_cvt_pk_bf16_f32 v123, v124, v125
	v_pk_add_f32 v[124:125], v[126:127], 1.0 op_sel_hi:[1,0]
	v_pk_mul_f32 v[114:115], v[118:119], v[114:115]
	v_pk_mul_f32 v[118:119], v[150:151], v[192:193] op_sel_hi:[1,0]
	v_rcp_f32_e32 v124, v124
	v_rcp_f32_e32 v125, v125
	v_pk_mul_f32 v[114:115], v[114:115], v[118:119]
	v_pk_mul_f32 v[118:119], v[148:149], v[186:187] op_sel_hi:[1,0]
	v_pk_mul_f32 v[146:147], v[184:185], v[188:189]
	v_pk_mul_f32 v[118:119], v[118:119], v[120:121]
	v_pk_mul_f32 v[114:115], v[114:115], v[124:125]
	v_exp_f32_e32 v118, v118
	v_exp_f32_e32 v119, v119
	v_cvt_pk_bf16_f32 v124, v114, v115
	v_cvt_f32_i32_e32 v115, v117
	v_cvt_f32_i32_e32 v114, v116
	v_pk_add_f32 v[116:117], v[118:119], 1.0 op_sel_hi:[1,0]
	v_pk_mul_f32 v[118:119], v[146:147], v[192:193] op_sel_hi:[1,0]
	v_rcp_f32_e32 v116, v116
	v_rcp_f32_e32 v117, v117
	v_pk_mul_f32 v[114:115], v[120:121], v[114:115]
	v_lshl_or_b32 v184, s66, 7, v177
	s_lshl_b32 s19, s26, 8
	v_pk_mul_f32 v[114:115], v[114:115], v[118:119]
	v_ashrrev_i32_e32 v185, 31, v184
	v_add_u32_e32 v183, s19, v167
	v_mov_b64_e32 v[162:163], s[60:61]
	v_pk_mul_f32 v[114:115], v[114:115], v[116:117]
	v_mad_i64_i32 v[188:189], s[28:29], v183, s64, v[162:163]
	v_cvt_pk_bf16_f32 v125, v114, v115
	v_lshlrev_b64 v[114:115], 1, v[184:185]
	v_lshl_add_u64 v[116:117], v[188:189], 0, v[114:115]
	global_store_dwordx4 v[116:117], v[122:125], off sc1 nt
	ds_read_b32 v116, v182 offset:64
	v_cvt_f32_i32_e32 v111, v111
	v_cvt_f32_i32_e32 v110, v110
	v_cvt_f32_i32_e32 v107, v107
	v_cvt_f32_i32_e32 v106, v106
	v_add_u32_e32 v117, s19, v170
	v_cvt_f32_i32_e32 v113, v113
	v_cvt_f32_i32_e32 v112, v112
	s_waitcnt lgkmcnt(0)
	v_pk_mul_f32 v[120:121], v[160:161], v[116:117] op_sel_hi:[1,0]
	v_mul_f32_e32 v122, v116, v116
	v_pk_mul_f32 v[120:121], v[120:121], v[110:111]
	v_pk_mul_f32 v[106:107], v[110:111], v[106:107]
	v_pk_mul_f32 v[110:111], v[158:159], v[122:123] op_sel_hi:[1,0]
	v_cvt_f32_i32_e32 v109, v109
	v_pk_mul_f32 v[106:107], v[106:107], v[110:111]
	v_pk_mul_f32 v[110:111], v[156:157], v[116:117] op_sel_hi:[1,0]
	v_cvt_f32_i32_e32 v108, v108
	v_pk_mul_f32 v[110:111], v[110:111], v[112:113]
	v_exp_f32_e32 v120, v120
	v_exp_f32_e32 v110, v110
	v_exp_f32_e32 v111, v111
	v_exp_f32_e32 v121, v121
	v_cvt_f32_i32_e32 v103, v103
	v_cvt_f32_i32_e32 v102, v102
	v_pk_add_f32 v[110:111], v[110:111], 1.0 op_sel_hi:[1,0]
	v_pk_mul_f32 v[108:109], v[112:113], v[108:109]
	v_rcp_f32_e32 v110, v110
	v_rcp_f32_e32 v111, v111
	v_pk_mul_f32 v[112:113], v[154:155], v[122:123] op_sel_hi:[1,0]
	v_pk_add_f32 v[120:121], v[120:121], 1.0 op_sel_hi:[1,0]
	v_pk_mul_f32 v[108:109], v[108:109], v[112:113]
	v_rcp_f32_e32 v120, v120
	v_pk_mul_f32 v[108:109], v[108:109], v[110:111]
	v_pk_mul_f32 v[110:111], v[152:153], v[116:117] op_sel_hi:[1,0]
	v_rcp_f32_e32 v121, v121
	v_pk_mul_f32 v[110:111], v[110:111], v[102:103]
	v_cvt_f32_i32_e32 v99, v99
	v_exp_f32_e32 v110, v110
	v_exp_f32_e32 v111, v111
	v_cvt_f32_i32_e32 v98, v98
	v_cvt_f32_i32_e32 v105, v105
	v_cvt_f32_i32_e32 v104, v104
	v_pk_mul_f32 v[106:107], v[106:107], v[120:121]
	v_pk_mul_f32 v[98:99], v[102:103], v[98:99]
	v_cvt_pk_bf16_f32 v106, v106, v107
	v_cvt_pk_bf16_f32 v107, v108, v109
	v_pk_add_f32 v[108:109], v[110:111], 1.0 op_sel_hi:[1,0]
	v_pk_mul_f32 v[102:103], v[150:151], v[122:123] op_sel_hi:[1,0]
	v_rcp_f32_e32 v108, v108
	v_rcp_f32_e32 v109, v109
	v_pk_mul_f32 v[98:99], v[98:99], v[102:103]
	v_pk_mul_f32 v[102:103], v[148:149], v[116:117] op_sel_hi:[1,0]
	v_mad_i64_i32 v[118:119], s[28:29], v117, s64, v[162:163]
	v_pk_mul_f32 v[102:103], v[102:103], v[104:105]
	v_pk_mul_f32 v[98:99], v[98:99], v[108:109]
	v_exp_f32_e32 v102, v102
	v_exp_f32_e32 v103, v103
	v_cvt_pk_bf16_f32 v108, v98, v99
	v_cvt_f32_i32_e32 v99, v101
	v_cvt_f32_i32_e32 v98, v100
	v_pk_add_f32 v[100:101], v[102:103], 1.0 op_sel_hi:[1,0]
	v_pk_mul_f32 v[102:103], v[146:147], v[122:123] op_sel_hi:[1,0]
	v_rcp_f32_e32 v100, v100
	v_rcp_f32_e32 v101, v101
	v_pk_mul_f32 v[98:99], v[104:105], v[98:99]
	v_cvt_f32_i32_e32 v95, v95
	v_pk_mul_f32 v[98:99], v[98:99], v[102:103]
	v_cvt_f32_i32_e32 v94, v94
	v_pk_mul_f32 v[98:99], v[98:99], v[100:101]
	v_cvt_f32_i32_e32 v91, v91
	v_cvt_pk_bf16_f32 v109, v98, v99
	v_lshl_add_u64 v[98:99], v[118:119], 0, v[114:115]
	global_store_dwordx4 v[98:99], v[106:109], off sc1 nt
	ds_read_b32 v98, v182 offset:128
	v_cvt_f32_i32_e32 v90, v90
	v_add_u32_e32 v99, s19, v171
	v_cvt_f32_i32_e32 v97, v97
	v_cvt_f32_i32_e32 v96, v96
	s_waitcnt lgkmcnt(0)
	v_pk_mul_f32 v[102:103], v[160:161], v[98:99] op_sel_hi:[1,0]
	v_mul_f32_e32 v104, v98, v98
	v_pk_mul_f32 v[102:103], v[102:103], v[94:95]
	v_pk_mul_f32 v[90:91], v[94:95], v[90:91]
	v_pk_mul_f32 v[94:95], v[158:159], v[104:105] op_sel_hi:[1,0]
	v_cvt_f32_i32_e32 v93, v93
	v_pk_mul_f32 v[90:91], v[90:91], v[94:95]
	v_pk_mul_f32 v[94:95], v[156:157], v[98:99] op_sel_hi:[1,0]
	v_cvt_f32_i32_e32 v92, v92
	v_pk_mul_f32 v[94:95], v[94:95], v[96:97]
	v_exp_f32_e32 v102, v102
	v_exp_f32_e32 v94, v94
	v_exp_f32_e32 v95, v95
	v_exp_f32_e32 v103, v103
	v_cvt_f32_i32_e32 v87, v87
	v_cvt_f32_i32_e32 v86, v86
	v_pk_add_f32 v[94:95], v[94:95], 1.0 op_sel_hi:[1,0]
	v_pk_mul_f32 v[92:93], v[96:97], v[92:93]
	v_rcp_f32_e32 v94, v94
	v_rcp_f32_e32 v95, v95
	v_pk_mul_f32 v[96:97], v[154:155], v[104:105] op_sel_hi:[1,0]
	v_pk_add_f32 v[102:103], v[102:103], 1.0 op_sel_hi:[1,0]
	v_pk_mul_f32 v[92:93], v[92:93], v[96:97]
	v_rcp_f32_e32 v102, v102
	v_pk_mul_f32 v[92:93], v[92:93], v[94:95]
	v_pk_mul_f32 v[94:95], v[152:153], v[98:99] op_sel_hi:[1,0]
	v_rcp_f32_e32 v103, v103
	v_pk_mul_f32 v[94:95], v[94:95], v[86:87]
	v_cvt_f32_i32_e32 v83, v83
	v_exp_f32_e32 v94, v94
	v_exp_f32_e32 v95, v95
	v_cvt_f32_i32_e32 v82, v82
	v_cvt_f32_i32_e32 v89, v89
	v_cvt_f32_i32_e32 v88, v88
	v_pk_mul_f32 v[90:91], v[90:91], v[102:103]
	v_pk_mul_f32 v[82:83], v[86:87], v[82:83]
	v_cvt_pk_bf16_f32 v90, v90, v91
	v_cvt_pk_bf16_f32 v91, v92, v93
	v_pk_add_f32 v[92:93], v[94:95], 1.0 op_sel_hi:[1,0]
	v_pk_mul_f32 v[86:87], v[150:151], v[104:105] op_sel_hi:[1,0]
	v_rcp_f32_e32 v92, v92
	v_rcp_f32_e32 v93, v93
	v_pk_mul_f32 v[82:83], v[82:83], v[86:87]
	v_pk_mul_f32 v[86:87], v[148:149], v[98:99] op_sel_hi:[1,0]
	v_mad_i64_i32 v[100:101], s[28:29], v99, s64, v[162:163]
	v_pk_mul_f32 v[86:87], v[86:87], v[88:89]
	v_pk_mul_f32 v[82:83], v[82:83], v[92:93]
	v_exp_f32_e32 v86, v86
	v_exp_f32_e32 v87, v87
	v_cvt_pk_bf16_f32 v92, v82, v83
	v_cvt_f32_i32_e32 v83, v85
	v_cvt_f32_i32_e32 v82, v84
	v_pk_add_f32 v[84:85], v[86:87], 1.0 op_sel_hi:[1,0]
	v_pk_mul_f32 v[86:87], v[146:147], v[104:105] op_sel_hi:[1,0]
	v_rcp_f32_e32 v84, v84
	v_rcp_f32_e32 v85, v85
	v_pk_mul_f32 v[82:83], v[88:89], v[82:83]
	v_cvt_f32_i32_e32 v79, v79
	v_pk_mul_f32 v[82:83], v[82:83], v[86:87]
	v_cvt_f32_i32_e32 v78, v78
	v_pk_mul_f32 v[82:83], v[82:83], v[84:85]
	v_cvt_f32_i32_e32 v75, v75
	v_cvt_pk_bf16_f32 v93, v82, v83
	v_lshl_add_u64 v[82:83], v[100:101], 0, v[114:115]
	global_store_dwordx4 v[82:83], v[90:93], off sc1 nt
	ds_read_b32 v82, v182 offset:192
	v_cvt_f32_i32_e32 v74, v74
	v_add_u32_e32 v83, s19, v172
	v_cvt_f32_i32_e32 v81, v81
	v_cvt_f32_i32_e32 v80, v80
	s_waitcnt lgkmcnt(0)
	v_pk_mul_f32 v[86:87], v[160:161], v[82:83] op_sel_hi:[1,0]
	v_mul_f32_e32 v88, v82, v82
	v_pk_mul_f32 v[86:87], v[86:87], v[78:79]
	v_pk_mul_f32 v[74:75], v[78:79], v[74:75]
	v_pk_mul_f32 v[78:79], v[158:159], v[88:89] op_sel_hi:[1,0]
	v_cvt_f32_i32_e32 v77, v77
	v_pk_mul_f32 v[74:75], v[74:75], v[78:79]
	v_pk_mul_f32 v[78:79], v[156:157], v[82:83] op_sel_hi:[1,0]
	v_cvt_f32_i32_e32 v76, v76
	v_pk_mul_f32 v[78:79], v[78:79], v[80:81]
	v_exp_f32_e32 v86, v86
	v_exp_f32_e32 v78, v78
	v_exp_f32_e32 v79, v79
	v_exp_f32_e32 v87, v87
	v_cvt_f32_i32_e32 v71, v71
	v_cvt_f32_i32_e32 v70, v70
	v_pk_add_f32 v[78:79], v[78:79], 1.0 op_sel_hi:[1,0]
	v_pk_mul_f32 v[76:77], v[80:81], v[76:77]
	v_rcp_f32_e32 v78, v78
	v_rcp_f32_e32 v79, v79
	v_pk_mul_f32 v[80:81], v[154:155], v[88:89] op_sel_hi:[1,0]
	v_pk_add_f32 v[86:87], v[86:87], 1.0 op_sel_hi:[1,0]
	v_pk_mul_f32 v[76:77], v[76:77], v[80:81]
	v_rcp_f32_e32 v86, v86
	v_pk_mul_f32 v[76:77], v[76:77], v[78:79]
	v_pk_mul_f32 v[78:79], v[152:153], v[82:83] op_sel_hi:[1,0]
	v_rcp_f32_e32 v87, v87
	v_pk_mul_f32 v[78:79], v[78:79], v[70:71]
	v_cvt_f32_i32_e32 v67, v67
	v_exp_f32_e32 v78, v78
	v_exp_f32_e32 v79, v79
	v_cvt_f32_i32_e32 v66, v66
	v_cvt_f32_i32_e32 v73, v73
	v_cvt_f32_i32_e32 v72, v72
	v_pk_mul_f32 v[74:75], v[74:75], v[86:87]
	v_pk_mul_f32 v[66:67], v[70:71], v[66:67]
	v_cvt_pk_bf16_f32 v74, v74, v75
	v_cvt_pk_bf16_f32 v75, v76, v77
	v_pk_add_f32 v[76:77], v[78:79], 1.0 op_sel_hi:[1,0]
	v_pk_mul_f32 v[70:71], v[150:151], v[88:89] op_sel_hi:[1,0]
	v_rcp_f32_e32 v76, v76
	v_rcp_f32_e32 v77, v77
	v_pk_mul_f32 v[66:67], v[66:67], v[70:71]
	v_pk_mul_f32 v[70:71], v[148:149], v[82:83] op_sel_hi:[1,0]
	v_mad_i64_i32 v[84:85], s[28:29], v83, s64, v[162:163]
	v_pk_mul_f32 v[70:71], v[70:71], v[72:73]
	v_pk_mul_f32 v[66:67], v[66:67], v[76:77]
	v_exp_f32_e32 v70, v70
	v_exp_f32_e32 v71, v71
	v_cvt_pk_bf16_f32 v76, v66, v67
	v_cvt_f32_i32_e32 v67, v69
	v_cvt_f32_i32_e32 v66, v68
	v_pk_add_f32 v[68:69], v[70:71], 1.0 op_sel_hi:[1,0]
	v_pk_mul_f32 v[70:71], v[146:147], v[88:89] op_sel_hi:[1,0]
	v_rcp_f32_e32 v68, v68
	v_rcp_f32_e32 v69, v69
	v_pk_mul_f32 v[66:67], v[72:73], v[66:67]
	v_cvt_f32_i32_e32 v63, v63
	v_pk_mul_f32 v[66:67], v[66:67], v[70:71]
	v_cvt_f32_i32_e32 v62, v62
	v_pk_mul_f32 v[66:67], v[66:67], v[68:69]
	v_cvt_f32_i32_e32 v59, v59
	v_cvt_pk_bf16_f32 v77, v66, v67
	v_lshl_add_u64 v[66:67], v[84:85], 0, v[114:115]
	global_store_dwordx4 v[66:67], v[74:77], off sc1 nt
	ds_read_b32 v66, v182 offset:512
	v_cvt_f32_i32_e32 v58, v58
	v_add_u32_e32 v67, s19, v173
	v_cvt_f32_i32_e32 v65, v65
	v_cvt_f32_i32_e32 v64, v64
	s_waitcnt lgkmcnt(0)
	v_pk_mul_f32 v[70:71], v[160:161], v[66:67] op_sel_hi:[1,0]
	v_mul_f32_e32 v72, v66, v66
	v_pk_mul_f32 v[70:71], v[70:71], v[62:63]
	v_pk_mul_f32 v[58:59], v[62:63], v[58:59]
	v_pk_mul_f32 v[62:63], v[158:159], v[72:73] op_sel_hi:[1,0]
	v_cvt_f32_i32_e32 v61, v61
	v_pk_mul_f32 v[58:59], v[58:59], v[62:63]
	v_pk_mul_f32 v[62:63], v[156:157], v[66:67] op_sel_hi:[1,0]
	v_cvt_f32_i32_e32 v60, v60
	v_pk_mul_f32 v[62:63], v[62:63], v[64:65]
	v_exp_f32_e32 v70, v70
	v_exp_f32_e32 v62, v62
	v_exp_f32_e32 v63, v63
	v_exp_f32_e32 v71, v71
	v_cvt_f32_i32_e32 v55, v55
	v_cvt_f32_i32_e32 v54, v54
	v_pk_add_f32 v[62:63], v[62:63], 1.0 op_sel_hi:[1,0]
	v_pk_mul_f32 v[60:61], v[64:65], v[60:61]
	v_rcp_f32_e32 v62, v62
	v_rcp_f32_e32 v63, v63
	v_pk_mul_f32 v[64:65], v[154:155], v[72:73] op_sel_hi:[1,0]
	v_pk_add_f32 v[70:71], v[70:71], 1.0 op_sel_hi:[1,0]
	v_pk_mul_f32 v[60:61], v[60:61], v[64:65]
	v_rcp_f32_e32 v70, v70
	v_pk_mul_f32 v[60:61], v[60:61], v[62:63]
	v_pk_mul_f32 v[62:63], v[152:153], v[66:67] op_sel_hi:[1,0]
	v_rcp_f32_e32 v71, v71
	v_pk_mul_f32 v[62:63], v[62:63], v[54:55]
	v_cvt_f32_i32_e32 v51, v51
	v_exp_f32_e32 v62, v62
	v_exp_f32_e32 v63, v63
	v_cvt_f32_i32_e32 v50, v50
	v_cvt_f32_i32_e32 v57, v57
	v_cvt_f32_i32_e32 v56, v56
	v_pk_mul_f32 v[58:59], v[58:59], v[70:71]
	v_pk_mul_f32 v[50:51], v[54:55], v[50:51]
	v_cvt_pk_bf16_f32 v58, v58, v59
	v_cvt_pk_bf16_f32 v59, v60, v61
	v_pk_add_f32 v[60:61], v[62:63], 1.0 op_sel_hi:[1,0]
	v_pk_mul_f32 v[54:55], v[150:151], v[72:73] op_sel_hi:[1,0]
	v_rcp_f32_e32 v60, v60
	v_rcp_f32_e32 v61, v61
	v_pk_mul_f32 v[50:51], v[50:51], v[54:55]
	v_pk_mul_f32 v[54:55], v[148:149], v[66:67] op_sel_hi:[1,0]
	v_mad_i64_i32 v[68:69], s[28:29], v67, s64, v[162:163]
	v_pk_mul_f32 v[54:55], v[54:55], v[56:57]
	v_pk_mul_f32 v[50:51], v[50:51], v[60:61]
	v_exp_f32_e32 v54, v54
	v_exp_f32_e32 v55, v55
	v_cvt_pk_bf16_f32 v60, v50, v51
	v_cvt_f32_i32_e32 v51, v53
	v_cvt_f32_i32_e32 v50, v52
	v_pk_add_f32 v[52:53], v[54:55], 1.0 op_sel_hi:[1,0]
	v_pk_mul_f32 v[54:55], v[146:147], v[72:73] op_sel_hi:[1,0]
	v_rcp_f32_e32 v52, v52
	v_rcp_f32_e32 v53, v53
	v_pk_mul_f32 v[50:51], v[56:57], v[50:51]
	v_cvt_f32_i32_e32 v47, v47
	v_pk_mul_f32 v[50:51], v[50:51], v[54:55]
	v_cvt_f32_i32_e32 v46, v46
	v_pk_mul_f32 v[50:51], v[50:51], v[52:53]
	v_cvt_f32_i32_e32 v43, v43
	v_cvt_pk_bf16_f32 v61, v50, v51
	v_lshl_add_u64 v[50:51], v[68:69], 0, v[114:115]
	global_store_dwordx4 v[50:51], v[58:61], off sc1 nt
	ds_read_b32 v50, v182 offset:576
	v_cvt_f32_i32_e32 v42, v42
	v_add_u32_e32 v51, s19, v174
	v_cvt_f32_i32_e32 v49, v49
	v_cvt_f32_i32_e32 v48, v48
	s_waitcnt lgkmcnt(0)
	v_pk_mul_f32 v[54:55], v[160:161], v[50:51] op_sel_hi:[1,0]
	v_mul_f32_e32 v56, v50, v50
	v_pk_mul_f32 v[54:55], v[54:55], v[46:47]
	v_pk_mul_f32 v[42:43], v[46:47], v[42:43]
	v_pk_mul_f32 v[46:47], v[158:159], v[56:57] op_sel_hi:[1,0]
	v_cvt_f32_i32_e32 v45, v45
	v_pk_mul_f32 v[42:43], v[42:43], v[46:47]
	v_pk_mul_f32 v[46:47], v[156:157], v[50:51] op_sel_hi:[1,0]
	v_cvt_f32_i32_e32 v44, v44
	v_pk_mul_f32 v[46:47], v[46:47], v[48:49]
	v_exp_f32_e32 v54, v54
	v_exp_f32_e32 v46, v46
	v_exp_f32_e32 v47, v47
	v_exp_f32_e32 v55, v55
	v_cvt_f32_i32_e32 v39, v39
	v_cvt_f32_i32_e32 v38, v38
	v_pk_add_f32 v[46:47], v[46:47], 1.0 op_sel_hi:[1,0]
	v_pk_mul_f32 v[44:45], v[48:49], v[44:45]
	v_rcp_f32_e32 v46, v46
	v_rcp_f32_e32 v47, v47
	v_pk_mul_f32 v[48:49], v[154:155], v[56:57] op_sel_hi:[1,0]
	v_pk_add_f32 v[54:55], v[54:55], 1.0 op_sel_hi:[1,0]
	v_pk_mul_f32 v[44:45], v[44:45], v[48:49]
	v_rcp_f32_e32 v54, v54
	v_pk_mul_f32 v[44:45], v[44:45], v[46:47]
	v_pk_mul_f32 v[46:47], v[152:153], v[50:51] op_sel_hi:[1,0]
	v_rcp_f32_e32 v55, v55
	v_pk_mul_f32 v[46:47], v[46:47], v[38:39]
	v_cvt_f32_i32_e32 v35, v35
	v_exp_f32_e32 v46, v46
	v_exp_f32_e32 v47, v47
	v_cvt_f32_i32_e32 v34, v34
	v_cvt_f32_i32_e32 v41, v41
	v_cvt_f32_i32_e32 v40, v40
	v_pk_mul_f32 v[42:43], v[42:43], v[54:55]
	v_pk_mul_f32 v[34:35], v[38:39], v[34:35]
	v_cvt_pk_bf16_f32 v42, v42, v43
	v_cvt_pk_bf16_f32 v43, v44, v45
	v_pk_add_f32 v[44:45], v[46:47], 1.0 op_sel_hi:[1,0]
	v_pk_mul_f32 v[38:39], v[150:151], v[56:57] op_sel_hi:[1,0]
	v_rcp_f32_e32 v44, v44
	v_rcp_f32_e32 v45, v45
	v_pk_mul_f32 v[34:35], v[34:35], v[38:39]
	v_pk_mul_f32 v[38:39], v[148:149], v[50:51] op_sel_hi:[1,0]
	v_mad_i64_i32 v[52:53], s[28:29], v51, s64, v[162:163]
	v_pk_mul_f32 v[38:39], v[38:39], v[40:41]
	v_pk_mul_f32 v[34:35], v[34:35], v[44:45]
	v_exp_f32_e32 v38, v38
	v_exp_f32_e32 v39, v39
	v_cvt_pk_bf16_f32 v44, v34, v35
	v_cvt_f32_i32_e32 v35, v37
	v_cvt_f32_i32_e32 v34, v36
	v_pk_add_f32 v[36:37], v[38:39], 1.0 op_sel_hi:[1,0]
	v_pk_mul_f32 v[38:39], v[146:147], v[56:57] op_sel_hi:[1,0]
	v_rcp_f32_e32 v36, v36
	v_rcp_f32_e32 v37, v37
	v_pk_mul_f32 v[34:35], v[40:41], v[34:35]
	v_cvt_f32_i32_e32 v31, v31
	v_pk_mul_f32 v[34:35], v[34:35], v[38:39]
	v_cvt_f32_i32_e32 v30, v30
	v_pk_mul_f32 v[34:35], v[34:35], v[36:37]
	v_cvt_f32_i32_e32 v27, v27
	v_cvt_pk_bf16_f32 v45, v34, v35
	v_lshl_add_u64 v[34:35], v[52:53], 0, v[114:115]
	global_store_dwordx4 v[34:35], v[42:45], off sc1 nt
	ds_read_b32 v34, v182 offset:640
	v_cvt_f32_i32_e32 v26, v26
	v_add_u32_e32 v35, s19, v175
	v_cvt_f32_i32_e32 v33, v33
	v_cvt_f32_i32_e32 v32, v32
	s_waitcnt lgkmcnt(0)
	v_pk_mul_f32 v[38:39], v[160:161], v[34:35] op_sel_hi:[1,0]
	v_mul_f32_e32 v40, v34, v34
	v_pk_mul_f32 v[38:39], v[38:39], v[30:31]
	v_pk_mul_f32 v[26:27], v[30:31], v[26:27]
	v_pk_mul_f32 v[30:31], v[158:159], v[40:41] op_sel_hi:[1,0]
	v_cvt_f32_i32_e32 v29, v29
	v_pk_mul_f32 v[26:27], v[26:27], v[30:31]
	v_pk_mul_f32 v[30:31], v[156:157], v[34:35] op_sel_hi:[1,0]
	v_cvt_f32_i32_e32 v28, v28
	v_pk_mul_f32 v[30:31], v[30:31], v[32:33]
	v_exp_f32_e32 v38, v38
	v_exp_f32_e32 v30, v30
	v_exp_f32_e32 v31, v31
	v_exp_f32_e32 v39, v39
	v_cvt_f32_i32_e32 v23, v23
	v_cvt_f32_i32_e32 v22, v22
	v_pk_add_f32 v[30:31], v[30:31], 1.0 op_sel_hi:[1,0]
	v_pk_mul_f32 v[28:29], v[32:33], v[28:29]
	v_rcp_f32_e32 v30, v30
	v_rcp_f32_e32 v31, v31
	v_pk_mul_f32 v[32:33], v[154:155], v[40:41] op_sel_hi:[1,0]
	v_pk_add_f32 v[38:39], v[38:39], 1.0 op_sel_hi:[1,0]
	v_pk_mul_f32 v[28:29], v[28:29], v[32:33]
	v_rcp_f32_e32 v38, v38
	v_pk_mul_f32 v[28:29], v[28:29], v[30:31]
	v_pk_mul_f32 v[30:31], v[152:153], v[34:35] op_sel_hi:[1,0]
	v_rcp_f32_e32 v39, v39
	v_pk_mul_f32 v[30:31], v[30:31], v[22:23]
	v_cvt_f32_i32_e32 v19, v19
	v_exp_f32_e32 v30, v30
	v_exp_f32_e32 v31, v31
	v_cvt_f32_i32_e32 v18, v18
	v_cvt_f32_i32_e32 v25, v25
	v_cvt_f32_i32_e32 v24, v24
	v_pk_mul_f32 v[26:27], v[26:27], v[38:39]
	v_pk_mul_f32 v[18:19], v[22:23], v[18:19]
	v_cvt_pk_bf16_f32 v26, v26, v27
	v_cvt_pk_bf16_f32 v27, v28, v29
	v_pk_add_f32 v[28:29], v[30:31], 1.0 op_sel_hi:[1,0]
	v_pk_mul_f32 v[22:23], v[150:151], v[40:41] op_sel_hi:[1,0]
	v_rcp_f32_e32 v28, v28
	v_rcp_f32_e32 v29, v29
	v_pk_mul_f32 v[18:19], v[18:19], v[22:23]
	v_pk_mul_f32 v[22:23], v[148:149], v[34:35] op_sel_hi:[1,0]
	v_mad_i64_i32 v[36:37], s[28:29], v35, s64, v[162:163]
	v_pk_mul_f32 v[22:23], v[22:23], v[24:25]
	v_pk_mul_f32 v[18:19], v[18:19], v[28:29]
	v_exp_f32_e32 v22, v22
	v_exp_f32_e32 v23, v23
	v_cvt_pk_bf16_f32 v28, v18, v19
	v_cvt_f32_i32_e32 v19, v21
	v_cvt_f32_i32_e32 v18, v20
	v_pk_add_f32 v[20:21], v[22:23], 1.0 op_sel_hi:[1,0]
	v_pk_mul_f32 v[22:23], v[146:147], v[40:41] op_sel_hi:[1,0]
	v_rcp_f32_e32 v20, v20
	v_rcp_f32_e32 v21, v21
	v_pk_mul_f32 v[18:19], v[24:25], v[18:19]
	v_cvt_f32_i32_e32 v15, v15
	v_pk_mul_f32 v[18:19], v[18:19], v[22:23]
	v_cvt_f32_i32_e32 v14, v14
	v_pk_mul_f32 v[18:19], v[18:19], v[20:21]
	v_cvt_f32_i32_e32 v11, v11
	v_cvt_pk_bf16_f32 v29, v18, v19
	v_lshl_add_u64 v[18:19], v[36:37], 0, v[114:115]
	global_store_dwordx4 v[18:19], v[26:29], off sc1 nt
	ds_read_b32 v18, v182 offset:704
	v_cvt_f32_i32_e32 v10, v10
	v_add_u32_e32 v19, s19, v176
	v_cvt_f32_i32_e32 v17, v17
	v_cvt_f32_i32_e32 v16, v16
	s_waitcnt lgkmcnt(0)
	v_pk_mul_f32 v[22:23], v[160:161], v[18:19] op_sel_hi:[1,0]
	v_mul_f32_e32 v24, v18, v18
	v_pk_mul_f32 v[22:23], v[22:23], v[14:15]
	v_pk_mul_f32 v[10:11], v[14:15], v[10:11]
	v_pk_mul_f32 v[14:15], v[158:159], v[24:25] op_sel_hi:[1,0]
	v_cvt_f32_i32_e32 v13, v13
	v_pk_mul_f32 v[10:11], v[10:11], v[14:15]
	v_pk_mul_f32 v[14:15], v[156:157], v[18:19] op_sel_hi:[1,0]
	v_cvt_f32_i32_e32 v12, v12
	v_pk_mul_f32 v[14:15], v[14:15], v[16:17]
	v_exp_f32_e32 v22, v22
	v_exp_f32_e32 v14, v14
	v_exp_f32_e32 v15, v15
	v_exp_f32_e32 v23, v23
	v_cvt_f32_i32_e32 v7, v7
	v_cvt_f32_i32_e32 v6, v6
	v_pk_add_f32 v[14:15], v[14:15], 1.0 op_sel_hi:[1,0]
	v_pk_mul_f32 v[12:13], v[16:17], v[12:13]
	v_rcp_f32_e32 v14, v14
	v_rcp_f32_e32 v15, v15
	v_pk_mul_f32 v[16:17], v[154:155], v[24:25] op_sel_hi:[1,0]
	v_pk_add_f32 v[22:23], v[22:23], 1.0 op_sel_hi:[1,0]
	v_pk_mul_f32 v[12:13], v[12:13], v[16:17]
	v_rcp_f32_e32 v22, v22
	v_pk_mul_f32 v[12:13], v[12:13], v[14:15]
	v_pk_mul_f32 v[14:15], v[152:153], v[18:19] op_sel_hi:[1,0]
	v_rcp_f32_e32 v23, v23
	v_pk_mul_f32 v[14:15], v[14:15], v[6:7]
	v_cvt_f32_i32_e32 v3, v3
	v_exp_f32_e32 v14, v14
	v_exp_f32_e32 v15, v15
	v_cvt_f32_i32_e32 v2, v2
	v_cvt_f32_i32_e32 v9, v9
	v_cvt_f32_i32_e32 v8, v8
	v_pk_mul_f32 v[10:11], v[10:11], v[22:23]
	v_pk_mul_f32 v[2:3], v[6:7], v[2:3]
	v_cvt_pk_bf16_f32 v10, v10, v11
	v_cvt_pk_bf16_f32 v11, v12, v13
	v_pk_add_f32 v[12:13], v[14:15], 1.0 op_sel_hi:[1,0]
	v_pk_mul_f32 v[6:7], v[150:151], v[24:25] op_sel_hi:[1,0]
	v_rcp_f32_e32 v12, v12
	v_rcp_f32_e32 v13, v13
	v_pk_mul_f32 v[2:3], v[2:3], v[6:7]
	v_pk_mul_f32 v[6:7], v[148:149], v[18:19] op_sel_hi:[1,0]
	v_mad_i64_i32 v[20:21], s[28:29], v19, s64, v[162:163]
	v_pk_mul_f32 v[6:7], v[6:7], v[8:9]
	v_pk_mul_f32 v[2:3], v[2:3], v[12:13]
	v_exp_f32_e32 v6, v6
	v_exp_f32_e32 v7, v7
	v_cvt_pk_bf16_f32 v12, v2, v3
	v_cvt_f32_i32_e32 v3, v5
	v_cvt_f32_i32_e32 v2, v4
	v_pk_add_f32 v[4:5], v[6:7], 1.0 op_sel_hi:[1,0]
	v_pk_mul_f32 v[6:7], v[146:147], v[24:25] op_sel_hi:[1,0]
	v_rcp_f32_e32 v4, v4
	v_rcp_f32_e32 v5, v5
	v_pk_mul_f32 v[2:3], v[8:9], v[2:3]
	s_andn2_b64 vcc, exec, s[4:5]
	v_pk_mul_f32 v[2:3], v[2:3], v[6:7]
	s_mov_b64 s[4:5], -1
	v_pk_mul_f32 v[2:3], v[2:3], v[4:5]
	s_nop 0
	v_cvt_pk_bf16_f32 v13, v2, v3
	v_lshl_add_u64 v[2:3], v[20:21], 0, v[114:115]
	global_store_dwordx4 v[2:3], v[10:13], off sc1 nt
	s_cbranch_vccnz .LBB0_133
	s_andn2_b64 vcc, exec, s[12:13]
	s_cbranch_vccnz .LBB0_132
	s_barrier
	s_branch .LBB0_132

.LBB0_740:
	s_lshl_b32 s19, s63, 11
	s_add_i32 s19, s19, 0
	s_add_i32 s21, s19, 0x20180
	s_lshl_b32 s19, s45, 2
	s_add_i32 s19, s21, s19
	v_lshl_add_u32 v154, v164, 2, s19
	ds_read_b128 v[146:149], v154 offset:1024
	ds_read_b128 v[150:153], v154 offset:1536
	ds_read_b128 v[182:185], v154 offset:1040
	ds_read_b128 v[186:189], v154 offset:1552
	v_cvt_f32_i32_e32 v127, v127
	v_cvt_f32_i32_e32 v126, v126
	s_waitcnt lgkmcnt(0)
	v_pk_mul_f32 v[154:155], v[148:149], v[152:153]
	v_pk_mul_f32 v[158:159], v[146:147], v[150:151]
	v_pk_mul_f32 v[152:153], v[182:183], s[16:17] op_sel_hi:[1,0]
	v_pk_mul_f32 v[150:151], v[182:183], v[186:187]
	v_lshl_add_u32 v182, v165, 2, s21
	ds_read_b32 v186, v182
	v_cvt_f32_i32_e32 v123, v123
	v_cvt_f32_i32_e32 v122, v122
	v_pk_mul_f32 v[160:161], v[146:147], s[16:17] op_sel_hi:[1,0]
	v_cvt_f32_i32_e32 v129, v129
	v_cvt_f32_i32_e32 v128, v128
	s_waitcnt lgkmcnt(0)
	v_pk_mul_f32 v[190:191], v[160:161], v[186:187] op_sel_hi:[1,0]
	v_mul_f32_e32 v192, v186, v186
	v_pk_mul_f32 v[156:157], v[148:149], s[16:17] op_sel_hi:[1,0]
	v_pk_mul_f32 v[190:191], v[190:191], v[126:127]
	v_pk_mul_f32 v[122:123], v[126:127], v[122:123]
	v_pk_mul_f32 v[126:127], v[158:159], v[192:193] op_sel_hi:[1,0]
	v_cvt_f32_i32_e32 v125, v125
	v_pk_mul_f32 v[122:123], v[122:123], v[126:127]
	v_pk_mul_f32 v[126:127], v[156:157], v[186:187] op_sel_hi:[1,0]
	v_cvt_f32_i32_e32 v124, v124
	v_pk_mul_f32 v[126:127], v[126:127], v[128:129]
	v_exp_f32_e32 v190, v190
	v_exp_f32_e32 v126, v126
	v_exp_f32_e32 v127, v127
	v_exp_f32_e32 v191, v191
	v_cvt_f32_i32_e32 v119, v119
	v_cvt_f32_i32_e32 v118, v118
	v_pk_add_f32 v[126:127], v[126:127], 1.0 op_sel_hi:[1,0]
	v_pk_mul_f32 v[124:125], v[128:129], v[124:125]
	v_rcp_f32_e32 v126, v126
	v_rcp_f32_e32 v127, v127
	v_pk_mul_f32 v[128:129], v[154:155], v[192:193] op_sel_hi:[1,0]
	v_pk_add_f32 v[190:191], v[190:191], 1.0 op_sel_hi:[1,0]
	v_pk_mul_f32 v[124:125], v[124:125], v[128:129]
	v_rcp_f32_e32 v190, v190
	v_pk_mul_f32 v[124:125], v[124:125], v[126:127]
	v_pk_mul_f32 v[126:127], v[152:153], v[186:187] op_sel_hi:[1,0]
	v_rcp_f32_e32 v191, v191
	v_pk_mul_f32 v[126:127], v[126:127], v[118:119]
	v_cvt_f32_i32_e32 v115, v115
	v_exp_f32_e32 v126, v126
	v_exp_f32_e32 v127, v127
	v_cvt_f32_i32_e32 v114, v114
	v_cvt_f32_i32_e32 v121, v121
	v_cvt_f32_i32_e32 v120, v120
	v_pk_mul_f32 v[122:123], v[122:123], v[190:191]
	v_pk_mul_f32 v[148:149], v[184:185], s[16:17] op_sel_hi:[1,0]
	v_cvt_pk_bf16_f32 v122, v122, v123
	v_cvt_pk_bf16_f32 v123, v124, v125
	v_pk_add_f32 v[124:125], v[126:127], 1.0 op_sel_hi:[1,0]
	v_pk_mul_f32 v[114:115], v[118:119], v[114:115]
	v_pk_mul_f32 v[118:119], v[150:151], v[192:193] op_sel_hi:[1,0]
	v_rcp_f32_e32 v124, v124
	v_rcp_f32_e32 v125, v125
	v_pk_mul_f32 v[114:115], v[114:115], v[118:119]
	v_pk_mul_f32 v[118:119], v[148:149], v[186:187] op_sel_hi:[1,0]
	v_pk_mul_f32 v[146:147], v[184:185], v[188:189]
	v_pk_mul_f32 v[118:119], v[118:119], v[120:121]
	v_pk_mul_f32 v[114:115], v[114:115], v[124:125]
	v_exp_f32_e32 v118, v118
	v_exp_f32_e32 v119, v119
	v_cvt_pk_bf16_f32 v124, v114, v115
	v_cvt_f32_i32_e32 v115, v117
	v_cvt_f32_i32_e32 v114, v116
	v_pk_add_f32 v[116:117], v[118:119], 1.0 op_sel_hi:[1,0]
	v_pk_mul_f32 v[118:119], v[146:147], v[192:193] op_sel_hi:[1,0]
	v_rcp_f32_e32 v116, v116
	v_rcp_f32_e32 v117, v117
	v_pk_mul_f32 v[114:115], v[120:121], v[114:115]
	v_lshl_or_b32 v184, s51, 7, v177
	s_lshl_b32 s19, s26, 8
	v_pk_mul_f32 v[114:115], v[114:115], v[118:119]
	v_ashrrev_i32_e32 v185, 31, v184
	v_add_u32_e32 v183, s19, v165
	v_mov_b64_e32 v[162:163], s[60:61]
	v_pk_mul_f32 v[114:115], v[114:115], v[116:117]
	v_mad_i64_i32 v[188:189], s[28:29], v183, s49, v[162:163]
	v_cvt_pk_bf16_f32 v125, v114, v115
	v_lshlrev_b64 v[114:115], 1, v[184:185]
	v_lshl_add_u64 v[116:117], v[188:189], 0, v[114:115]
	global_store_dwordx4 v[116:117], v[122:125], off sc1 nt
	ds_read_b32 v116, v182 offset:64
	v_cvt_f32_i32_e32 v111, v111
	v_cvt_f32_i32_e32 v110, v110
	v_cvt_f32_i32_e32 v107, v107
	v_cvt_f32_i32_e32 v106, v106
	v_add_u32_e32 v117, s19, v170
	v_cvt_f32_i32_e32 v113, v113
	v_cvt_f32_i32_e32 v112, v112
	s_waitcnt lgkmcnt(0)
	v_pk_mul_f32 v[120:121], v[160:161], v[116:117] op_sel_hi:[1,0]
	v_mul_f32_e32 v122, v116, v116
	v_pk_mul_f32 v[120:121], v[120:121], v[110:111]
	v_pk_mul_f32 v[106:107], v[110:111], v[106:107]
	v_pk_mul_f32 v[110:111], v[158:159], v[122:123] op_sel_hi:[1,0]
	v_cvt_f32_i32_e32 v109, v109
	v_pk_mul_f32 v[106:107], v[106:107], v[110:111]
	v_pk_mul_f32 v[110:111], v[156:157], v[116:117] op_sel_hi:[1,0]
	v_cvt_f32_i32_e32 v108, v108
	v_pk_mul_f32 v[110:111], v[110:111], v[112:113]
	v_exp_f32_e32 v120, v120
	v_exp_f32_e32 v110, v110
	v_exp_f32_e32 v111, v111
	v_exp_f32_e32 v121, v121
	v_cvt_f32_i32_e32 v103, v103
	v_cvt_f32_i32_e32 v102, v102
	v_pk_add_f32 v[110:111], v[110:111], 1.0 op_sel_hi:[1,0]
	v_pk_mul_f32 v[108:109], v[112:113], v[108:109]
	v_rcp_f32_e32 v110, v110
	v_rcp_f32_e32 v111, v111
	v_pk_mul_f32 v[112:113], v[154:155], v[122:123] op_sel_hi:[1,0]
	v_pk_add_f32 v[120:121], v[120:121], 1.0 op_sel_hi:[1,0]
	v_pk_mul_f32 v[108:109], v[108:109], v[112:113]
	v_rcp_f32_e32 v120, v120
	v_pk_mul_f32 v[108:109], v[108:109], v[110:111]
	v_pk_mul_f32 v[110:111], v[152:153], v[116:117] op_sel_hi:[1,0]
	v_rcp_f32_e32 v121, v121
	v_pk_mul_f32 v[110:111], v[110:111], v[102:103]
	v_cvt_f32_i32_e32 v99, v99
	v_exp_f32_e32 v110, v110
	v_exp_f32_e32 v111, v111
	v_cvt_f32_i32_e32 v98, v98
	v_cvt_f32_i32_e32 v105, v105
	v_cvt_f32_i32_e32 v104, v104
	v_pk_mul_f32 v[106:107], v[106:107], v[120:121]
	v_pk_mul_f32 v[98:99], v[102:103], v[98:99]
	v_cvt_pk_bf16_f32 v106, v106, v107
	v_cvt_pk_bf16_f32 v107, v108, v109
	v_pk_add_f32 v[108:109], v[110:111], 1.0 op_sel_hi:[1,0]
	v_pk_mul_f32 v[102:103], v[150:151], v[122:123] op_sel_hi:[1,0]
	v_rcp_f32_e32 v108, v108
	v_rcp_f32_e32 v109, v109
	v_pk_mul_f32 v[98:99], v[98:99], v[102:103]
	v_pk_mul_f32 v[102:103], v[148:149], v[116:117] op_sel_hi:[1,0]
	v_mad_i64_i32 v[118:119], s[28:29], v117, s49, v[162:163]
	v_pk_mul_f32 v[102:103], v[102:103], v[104:105]
	v_pk_mul_f32 v[98:99], v[98:99], v[108:109]
	v_exp_f32_e32 v102, v102
	v_exp_f32_e32 v103, v103
	v_cvt_pk_bf16_f32 v108, v98, v99
	v_cvt_f32_i32_e32 v99, v101
	v_cvt_f32_i32_e32 v98, v100
	v_pk_add_f32 v[100:101], v[102:103], 1.0 op_sel_hi:[1,0]
	v_pk_mul_f32 v[102:103], v[146:147], v[122:123] op_sel_hi:[1,0]
	v_rcp_f32_e32 v100, v100
	v_rcp_f32_e32 v101, v101
	v_pk_mul_f32 v[98:99], v[104:105], v[98:99]
	v_cvt_f32_i32_e32 v95, v95
	v_pk_mul_f32 v[98:99], v[98:99], v[102:103]
	v_cvt_f32_i32_e32 v94, v94
	v_pk_mul_f32 v[98:99], v[98:99], v[100:101]
	v_cvt_f32_i32_e32 v91, v91
	v_cvt_pk_bf16_f32 v109, v98, v99
	v_lshl_add_u64 v[98:99], v[118:119], 0, v[114:115]
	global_store_dwordx4 v[98:99], v[106:109], off sc1 nt
	ds_read_b32 v98, v182 offset:128
	v_cvt_f32_i32_e32 v90, v90
	v_add_u32_e32 v99, s19, v171
	v_cvt_f32_i32_e32 v97, v97
	v_cvt_f32_i32_e32 v96, v96
	s_waitcnt lgkmcnt(0)
	v_pk_mul_f32 v[102:103], v[160:161], v[98:99] op_sel_hi:[1,0]
	v_mul_f32_e32 v104, v98, v98
	v_pk_mul_f32 v[102:103], v[102:103], v[94:95]
	v_pk_mul_f32 v[90:91], v[94:95], v[90:91]
	v_pk_mul_f32 v[94:95], v[158:159], v[104:105] op_sel_hi:[1,0]
	v_cvt_f32_i32_e32 v93, v93
	v_pk_mul_f32 v[90:91], v[90:91], v[94:95]
	v_pk_mul_f32 v[94:95], v[156:157], v[98:99] op_sel_hi:[1,0]
	v_cvt_f32_i32_e32 v92, v92
	v_pk_mul_f32 v[94:95], v[94:95], v[96:97]
	v_exp_f32_e32 v102, v102
	v_exp_f32_e32 v94, v94
	v_exp_f32_e32 v95, v95
	v_exp_f32_e32 v103, v103
	v_cvt_f32_i32_e32 v87, v87
	v_cvt_f32_i32_e32 v86, v86
	v_pk_add_f32 v[94:95], v[94:95], 1.0 op_sel_hi:[1,0]
	v_pk_mul_f32 v[92:93], v[96:97], v[92:93]
	v_rcp_f32_e32 v94, v94
	v_rcp_f32_e32 v95, v95
	v_pk_mul_f32 v[96:97], v[154:155], v[104:105] op_sel_hi:[1,0]
	v_pk_add_f32 v[102:103], v[102:103], 1.0 op_sel_hi:[1,0]
	v_pk_mul_f32 v[92:93], v[92:93], v[96:97]
	v_rcp_f32_e32 v102, v102
	v_pk_mul_f32 v[92:93], v[92:93], v[94:95]
	v_pk_mul_f32 v[94:95], v[152:153], v[98:99] op_sel_hi:[1,0]
	v_rcp_f32_e32 v103, v103
	v_pk_mul_f32 v[94:95], v[94:95], v[86:87]
	v_cvt_f32_i32_e32 v83, v83
	v_exp_f32_e32 v94, v94
	v_exp_f32_e32 v95, v95
	v_cvt_f32_i32_e32 v82, v82
	v_cvt_f32_i32_e32 v89, v89
	v_cvt_f32_i32_e32 v88, v88
	v_pk_mul_f32 v[90:91], v[90:91], v[102:103]
	v_pk_mul_f32 v[82:83], v[86:87], v[82:83]
	v_cvt_pk_bf16_f32 v90, v90, v91
	v_cvt_pk_bf16_f32 v91, v92, v93
	v_pk_add_f32 v[92:93], v[94:95], 1.0 op_sel_hi:[1,0]
	v_pk_mul_f32 v[86:87], v[150:151], v[104:105] op_sel_hi:[1,0]
	v_rcp_f32_e32 v92, v92
	v_rcp_f32_e32 v93, v93
	v_pk_mul_f32 v[82:83], v[82:83], v[86:87]
	v_pk_mul_f32 v[86:87], v[148:149], v[98:99] op_sel_hi:[1,0]
	v_mad_i64_i32 v[100:101], s[28:29], v99, s49, v[162:163]
	v_pk_mul_f32 v[86:87], v[86:87], v[88:89]
	v_pk_mul_f32 v[82:83], v[82:83], v[92:93]
	v_exp_f32_e32 v86, v86
	v_exp_f32_e32 v87, v87
	v_cvt_pk_bf16_f32 v92, v82, v83
	v_cvt_f32_i32_e32 v83, v85
	v_cvt_f32_i32_e32 v82, v84
	v_pk_add_f32 v[84:85], v[86:87], 1.0 op_sel_hi:[1,0]
	v_pk_mul_f32 v[86:87], v[146:147], v[104:105] op_sel_hi:[1,0]
	v_rcp_f32_e32 v84, v84
	v_rcp_f32_e32 v85, v85
	v_pk_mul_f32 v[82:83], v[88:89], v[82:83]
	v_cvt_f32_i32_e32 v79, v79
	v_pk_mul_f32 v[82:83], v[82:83], v[86:87]
	v_cvt_f32_i32_e32 v78, v78
	v_pk_mul_f32 v[82:83], v[82:83], v[84:85]
	v_cvt_f32_i32_e32 v75, v75
	v_cvt_pk_bf16_f32 v93, v82, v83
	v_lshl_add_u64 v[82:83], v[100:101], 0, v[114:115]
	global_store_dwordx4 v[82:83], v[90:93], off sc1 nt
	ds_read_b32 v82, v182 offset:192
	v_cvt_f32_i32_e32 v74, v74
	v_add_u32_e32 v83, s19, v172
	v_cvt_f32_i32_e32 v81, v81
	v_cvt_f32_i32_e32 v80, v80
	s_waitcnt lgkmcnt(0)
	v_pk_mul_f32 v[86:87], v[160:161], v[82:83] op_sel_hi:[1,0]
	v_mul_f32_e32 v88, v82, v82
	v_pk_mul_f32 v[86:87], v[86:87], v[78:79]
	v_pk_mul_f32 v[74:75], v[78:79], v[74:75]
	v_pk_mul_f32 v[78:79], v[158:159], v[88:89] op_sel_hi:[1,0]
	v_cvt_f32_i32_e32 v77, v77
	v_pk_mul_f32 v[74:75], v[74:75], v[78:79]
	v_pk_mul_f32 v[78:79], v[156:157], v[82:83] op_sel_hi:[1,0]
	v_cvt_f32_i32_e32 v76, v76
	v_pk_mul_f32 v[78:79], v[78:79], v[80:81]
	v_exp_f32_e32 v86, v86
	v_exp_f32_e32 v78, v78
	v_exp_f32_e32 v79, v79
	v_exp_f32_e32 v87, v87
	v_cvt_f32_i32_e32 v71, v71
	v_cvt_f32_i32_e32 v70, v70
	v_pk_add_f32 v[78:79], v[78:79], 1.0 op_sel_hi:[1,0]
	v_pk_mul_f32 v[76:77], v[80:81], v[76:77]
	v_rcp_f32_e32 v78, v78
	v_rcp_f32_e32 v79, v79
	v_pk_mul_f32 v[80:81], v[154:155], v[88:89] op_sel_hi:[1,0]
	v_pk_add_f32 v[86:87], v[86:87], 1.0 op_sel_hi:[1,0]
	v_pk_mul_f32 v[76:77], v[76:77], v[80:81]
	v_rcp_f32_e32 v86, v86
	v_pk_mul_f32 v[76:77], v[76:77], v[78:79]
	v_pk_mul_f32 v[78:79], v[152:153], v[82:83] op_sel_hi:[1,0]
	v_rcp_f32_e32 v87, v87
	v_pk_mul_f32 v[78:79], v[78:79], v[70:71]
	v_cvt_f32_i32_e32 v67, v67
	v_exp_f32_e32 v78, v78
	v_exp_f32_e32 v79, v79
	v_cvt_f32_i32_e32 v66, v66
	v_cvt_f32_i32_e32 v73, v73
	v_cvt_f32_i32_e32 v72, v72
	v_pk_mul_f32 v[74:75], v[74:75], v[86:87]
	v_pk_mul_f32 v[66:67], v[70:71], v[66:67]
	v_cvt_pk_bf16_f32 v74, v74, v75
	v_cvt_pk_bf16_f32 v75, v76, v77
	v_pk_add_f32 v[76:77], v[78:79], 1.0 op_sel_hi:[1,0]
	v_pk_mul_f32 v[70:71], v[150:151], v[88:89] op_sel_hi:[1,0]
	v_rcp_f32_e32 v76, v76
	v_rcp_f32_e32 v77, v77
	v_pk_mul_f32 v[66:67], v[66:67], v[70:71]
	v_pk_mul_f32 v[70:71], v[148:149], v[82:83] op_sel_hi:[1,0]
	v_mad_i64_i32 v[84:85], s[28:29], v83, s49, v[162:163]
	v_pk_mul_f32 v[70:71], v[70:71], v[72:73]
	v_pk_mul_f32 v[66:67], v[66:67], v[76:77]
	v_exp_f32_e32 v70, v70
	v_exp_f32_e32 v71, v71
	v_cvt_pk_bf16_f32 v76, v66, v67
	v_cvt_f32_i32_e32 v67, v69
	v_cvt_f32_i32_e32 v66, v68
	v_pk_add_f32 v[68:69], v[70:71], 1.0 op_sel_hi:[1,0]
	v_pk_mul_f32 v[70:71], v[146:147], v[88:89] op_sel_hi:[1,0]
	v_rcp_f32_e32 v68, v68
	v_rcp_f32_e32 v69, v69
	v_pk_mul_f32 v[66:67], v[72:73], v[66:67]
	v_cvt_f32_i32_e32 v63, v63
	v_pk_mul_f32 v[66:67], v[66:67], v[70:71]
	v_cvt_f32_i32_e32 v62, v62
	v_pk_mul_f32 v[66:67], v[66:67], v[68:69]
	v_cvt_f32_i32_e32 v59, v59
	v_cvt_pk_bf16_f32 v77, v66, v67
	v_lshl_add_u64 v[66:67], v[84:85], 0, v[114:115]
	global_store_dwordx4 v[66:67], v[74:77], off sc1 nt
	ds_read_b32 v66, v182 offset:512
	v_cvt_f32_i32_e32 v58, v58
	v_add_u32_e32 v67, s19, v173
	v_cvt_f32_i32_e32 v65, v65
	v_cvt_f32_i32_e32 v64, v64
	s_waitcnt lgkmcnt(0)
	v_pk_mul_f32 v[70:71], v[160:161], v[66:67] op_sel_hi:[1,0]
	v_mul_f32_e32 v72, v66, v66
	v_pk_mul_f32 v[70:71], v[70:71], v[62:63]
	v_pk_mul_f32 v[58:59], v[62:63], v[58:59]
	v_pk_mul_f32 v[62:63], v[158:159], v[72:73] op_sel_hi:[1,0]
	v_cvt_f32_i32_e32 v61, v61
	v_pk_mul_f32 v[58:59], v[58:59], v[62:63]
	v_pk_mul_f32 v[62:63], v[156:157], v[66:67] op_sel_hi:[1,0]
	v_cvt_f32_i32_e32 v60, v60
	v_pk_mul_f32 v[62:63], v[62:63], v[64:65]
	v_exp_f32_e32 v70, v70
	v_exp_f32_e32 v62, v62
	v_exp_f32_e32 v63, v63
	v_exp_f32_e32 v71, v71
	v_cvt_f32_i32_e32 v55, v55
	v_cvt_f32_i32_e32 v54, v54
	v_pk_add_f32 v[62:63], v[62:63], 1.0 op_sel_hi:[1,0]
	v_pk_mul_f32 v[60:61], v[64:65], v[60:61]
	v_rcp_f32_e32 v62, v62
	v_rcp_f32_e32 v63, v63
	v_pk_mul_f32 v[64:65], v[154:155], v[72:73] op_sel_hi:[1,0]
	v_pk_add_f32 v[70:71], v[70:71], 1.0 op_sel_hi:[1,0]
	v_pk_mul_f32 v[60:61], v[60:61], v[64:65]
	v_rcp_f32_e32 v70, v70
	v_pk_mul_f32 v[60:61], v[60:61], v[62:63]
	v_pk_mul_f32 v[62:63], v[152:153], v[66:67] op_sel_hi:[1,0]
	v_rcp_f32_e32 v71, v71
	v_pk_mul_f32 v[62:63], v[62:63], v[54:55]
	v_cvt_f32_i32_e32 v51, v51
	v_exp_f32_e32 v62, v62
	v_exp_f32_e32 v63, v63
	v_cvt_f32_i32_e32 v50, v50
	v_cvt_f32_i32_e32 v57, v57
	v_cvt_f32_i32_e32 v56, v56
	v_pk_mul_f32 v[58:59], v[58:59], v[70:71]
	v_pk_mul_f32 v[50:51], v[54:55], v[50:51]
	v_cvt_pk_bf16_f32 v58, v58, v59
	v_cvt_pk_bf16_f32 v59, v60, v61
	v_pk_add_f32 v[60:61], v[62:63], 1.0 op_sel_hi:[1,0]
	v_pk_mul_f32 v[54:55], v[150:151], v[72:73] op_sel_hi:[1,0]
	v_rcp_f32_e32 v60, v60
	v_rcp_f32_e32 v61, v61
	v_pk_mul_f32 v[50:51], v[50:51], v[54:55]
	v_pk_mul_f32 v[54:55], v[148:149], v[66:67] op_sel_hi:[1,0]
	v_mad_i64_i32 v[68:69], s[28:29], v67, s49, v[162:163]
	v_pk_mul_f32 v[54:55], v[54:55], v[56:57]
	v_pk_mul_f32 v[50:51], v[50:51], v[60:61]
	v_exp_f32_e32 v54, v54
	v_exp_f32_e32 v55, v55
	v_cvt_pk_bf16_f32 v60, v50, v51
	v_cvt_f32_i32_e32 v51, v53
	v_cvt_f32_i32_e32 v50, v52
	v_pk_add_f32 v[52:53], v[54:55], 1.0 op_sel_hi:[1,0]
	v_pk_mul_f32 v[54:55], v[146:147], v[72:73] op_sel_hi:[1,0]
	v_rcp_f32_e32 v52, v52
	v_rcp_f32_e32 v53, v53
	v_pk_mul_f32 v[50:51], v[56:57], v[50:51]
	v_cvt_f32_i32_e32 v47, v47
	v_pk_mul_f32 v[50:51], v[50:51], v[54:55]
	v_cvt_f32_i32_e32 v46, v46
	v_pk_mul_f32 v[50:51], v[50:51], v[52:53]
	v_cvt_f32_i32_e32 v43, v43
	v_cvt_pk_bf16_f32 v61, v50, v51
	v_lshl_add_u64 v[50:51], v[68:69], 0, v[114:115]
	global_store_dwordx4 v[50:51], v[58:61], off sc1 nt
	ds_read_b32 v50, v182 offset:576
	v_cvt_f32_i32_e32 v42, v42
	v_add_u32_e32 v51, s19, v174
	v_cvt_f32_i32_e32 v49, v49
	v_cvt_f32_i32_e32 v48, v48
	s_waitcnt lgkmcnt(0)
	v_pk_mul_f32 v[54:55], v[160:161], v[50:51] op_sel_hi:[1,0]
	v_mul_f32_e32 v56, v50, v50
	v_pk_mul_f32 v[54:55], v[54:55], v[46:47]
	v_pk_mul_f32 v[42:43], v[46:47], v[42:43]
	v_pk_mul_f32 v[46:47], v[158:159], v[56:57] op_sel_hi:[1,0]
	v_cvt_f32_i32_e32 v45, v45
	v_pk_mul_f32 v[42:43], v[42:43], v[46:47]
	v_pk_mul_f32 v[46:47], v[156:157], v[50:51] op_sel_hi:[1,0]
	v_cvt_f32_i32_e32 v44, v44
	v_pk_mul_f32 v[46:47], v[46:47], v[48:49]
	v_exp_f32_e32 v54, v54
	v_exp_f32_e32 v46, v46
	v_exp_f32_e32 v47, v47
	v_exp_f32_e32 v55, v55
	v_cvt_f32_i32_e32 v39, v39
	v_cvt_f32_i32_e32 v38, v38
	v_pk_add_f32 v[46:47], v[46:47], 1.0 op_sel_hi:[1,0]
	v_pk_mul_f32 v[44:45], v[48:49], v[44:45]
	v_rcp_f32_e32 v46, v46
	v_rcp_f32_e32 v47, v47
	v_pk_mul_f32 v[48:49], v[154:155], v[56:57] op_sel_hi:[1,0]
	v_pk_add_f32 v[54:55], v[54:55], 1.0 op_sel_hi:[1,0]
	v_pk_mul_f32 v[44:45], v[44:45], v[48:49]
	v_rcp_f32_e32 v54, v54
	v_pk_mul_f32 v[44:45], v[44:45], v[46:47]
	v_pk_mul_f32 v[46:47], v[152:153], v[50:51] op_sel_hi:[1,0]
	v_rcp_f32_e32 v55, v55
	v_pk_mul_f32 v[46:47], v[46:47], v[38:39]
	v_cvt_f32_i32_e32 v35, v35
	v_exp_f32_e32 v46, v46
	v_exp_f32_e32 v47, v47
	v_cvt_f32_i32_e32 v34, v34
	v_cvt_f32_i32_e32 v41, v41
	v_cvt_f32_i32_e32 v40, v40
	v_pk_mul_f32 v[42:43], v[42:43], v[54:55]
	v_pk_mul_f32 v[34:35], v[38:39], v[34:35]
	v_cvt_pk_bf16_f32 v42, v42, v43
	v_cvt_pk_bf16_f32 v43, v44, v45
	v_pk_add_f32 v[44:45], v[46:47], 1.0 op_sel_hi:[1,0]
	v_pk_mul_f32 v[38:39], v[150:151], v[56:57] op_sel_hi:[1,0]
	v_rcp_f32_e32 v44, v44
	v_rcp_f32_e32 v45, v45
	v_pk_mul_f32 v[34:35], v[34:35], v[38:39]
	v_pk_mul_f32 v[38:39], v[148:149], v[50:51] op_sel_hi:[1,0]
	v_mad_i64_i32 v[52:53], s[28:29], v51, s49, v[162:163]
	v_pk_mul_f32 v[38:39], v[38:39], v[40:41]
	v_pk_mul_f32 v[34:35], v[34:35], v[44:45]
	v_exp_f32_e32 v38, v38
	v_exp_f32_e32 v39, v39
	v_cvt_pk_bf16_f32 v44, v34, v35
	v_cvt_f32_i32_e32 v35, v37
	v_cvt_f32_i32_e32 v34, v36
	v_pk_add_f32 v[36:37], v[38:39], 1.0 op_sel_hi:[1,0]
	v_pk_mul_f32 v[38:39], v[146:147], v[56:57] op_sel_hi:[1,0]
	v_rcp_f32_e32 v36, v36
	v_rcp_f32_e32 v37, v37
	v_pk_mul_f32 v[34:35], v[40:41], v[34:35]
	v_cvt_f32_i32_e32 v31, v31
	v_pk_mul_f32 v[34:35], v[34:35], v[38:39]
	v_cvt_f32_i32_e32 v30, v30
	v_pk_mul_f32 v[34:35], v[34:35], v[36:37]
	v_cvt_f32_i32_e32 v27, v27
	v_cvt_pk_bf16_f32 v45, v34, v35
	v_lshl_add_u64 v[34:35], v[52:53], 0, v[114:115]
	global_store_dwordx4 v[34:35], v[42:45], off sc1 nt
	ds_read_b32 v34, v182 offset:640
	v_cvt_f32_i32_e32 v26, v26
	v_add_u32_e32 v35, s19, v175
	v_cvt_f32_i32_e32 v33, v33
	v_cvt_f32_i32_e32 v32, v32
	s_waitcnt lgkmcnt(0)
	v_pk_mul_f32 v[38:39], v[160:161], v[34:35] op_sel_hi:[1,0]
	v_mul_f32_e32 v40, v34, v34
	v_pk_mul_f32 v[38:39], v[38:39], v[30:31]
	v_pk_mul_f32 v[26:27], v[30:31], v[26:27]
	v_pk_mul_f32 v[30:31], v[158:159], v[40:41] op_sel_hi:[1,0]
	v_cvt_f32_i32_e32 v29, v29
	v_pk_mul_f32 v[26:27], v[26:27], v[30:31]
	v_pk_mul_f32 v[30:31], v[156:157], v[34:35] op_sel_hi:[1,0]
	v_cvt_f32_i32_e32 v28, v28
	v_pk_mul_f32 v[30:31], v[30:31], v[32:33]
	v_exp_f32_e32 v38, v38
	v_exp_f32_e32 v30, v30
	v_exp_f32_e32 v31, v31
	v_exp_f32_e32 v39, v39
	v_cvt_f32_i32_e32 v23, v23
	v_cvt_f32_i32_e32 v22, v22
	v_pk_add_f32 v[30:31], v[30:31], 1.0 op_sel_hi:[1,0]
	v_pk_mul_f32 v[28:29], v[32:33], v[28:29]
	v_rcp_f32_e32 v30, v30
	v_rcp_f32_e32 v31, v31
	v_pk_mul_f32 v[32:33], v[154:155], v[40:41] op_sel_hi:[1,0]
	v_pk_add_f32 v[38:39], v[38:39], 1.0 op_sel_hi:[1,0]
	v_pk_mul_f32 v[28:29], v[28:29], v[32:33]
	v_rcp_f32_e32 v38, v38
	v_pk_mul_f32 v[28:29], v[28:29], v[30:31]
	v_pk_mul_f32 v[30:31], v[152:153], v[34:35] op_sel_hi:[1,0]
	v_rcp_f32_e32 v39, v39
	v_pk_mul_f32 v[30:31], v[30:31], v[22:23]
	v_cvt_f32_i32_e32 v19, v19
	v_exp_f32_e32 v30, v30
	v_exp_f32_e32 v31, v31
	v_cvt_f32_i32_e32 v18, v18
	v_cvt_f32_i32_e32 v25, v25
	v_cvt_f32_i32_e32 v24, v24
	v_pk_mul_f32 v[26:27], v[26:27], v[38:39]
	v_pk_mul_f32 v[18:19], v[22:23], v[18:19]
	v_cvt_pk_bf16_f32 v26, v26, v27
	v_cvt_pk_bf16_f32 v27, v28, v29
	v_pk_add_f32 v[28:29], v[30:31], 1.0 op_sel_hi:[1,0]
	v_pk_mul_f32 v[22:23], v[150:151], v[40:41] op_sel_hi:[1,0]
	v_rcp_f32_e32 v28, v28
	v_rcp_f32_e32 v29, v29
	v_pk_mul_f32 v[18:19], v[18:19], v[22:23]
	v_pk_mul_f32 v[22:23], v[148:149], v[34:35] op_sel_hi:[1,0]
	v_mad_i64_i32 v[36:37], s[28:29], v35, s49, v[162:163]
	v_pk_mul_f32 v[22:23], v[22:23], v[24:25]
	v_pk_mul_f32 v[18:19], v[18:19], v[28:29]
	v_exp_f32_e32 v22, v22
	v_exp_f32_e32 v23, v23
	v_cvt_pk_bf16_f32 v28, v18, v19
	v_cvt_f32_i32_e32 v19, v21
	v_cvt_f32_i32_e32 v18, v20
	v_pk_add_f32 v[20:21], v[22:23], 1.0 op_sel_hi:[1,0]
	v_pk_mul_f32 v[22:23], v[146:147], v[40:41] op_sel_hi:[1,0]
	v_rcp_f32_e32 v20, v20
	v_rcp_f32_e32 v21, v21
	v_pk_mul_f32 v[18:19], v[24:25], v[18:19]
	v_cvt_f32_i32_e32 v15, v15
	v_pk_mul_f32 v[18:19], v[18:19], v[22:23]
	v_cvt_f32_i32_e32 v14, v14
	v_pk_mul_f32 v[18:19], v[18:19], v[20:21]
	v_cvt_f32_i32_e32 v11, v11
	v_cvt_pk_bf16_f32 v29, v18, v19
	v_lshl_add_u64 v[18:19], v[36:37], 0, v[114:115]
	global_store_dwordx4 v[18:19], v[26:29], off sc1 nt
	ds_read_b32 v18, v182 offset:704
	v_cvt_f32_i32_e32 v10, v10
	v_add_u32_e32 v19, s19, v176
	v_cvt_f32_i32_e32 v17, v17
	v_cvt_f32_i32_e32 v16, v16
	s_waitcnt lgkmcnt(0)
	v_pk_mul_f32 v[22:23], v[160:161], v[18:19] op_sel_hi:[1,0]
	v_mul_f32_e32 v24, v18, v18
	v_pk_mul_f32 v[22:23], v[22:23], v[14:15]
	v_pk_mul_f32 v[10:11], v[14:15], v[10:11]
	v_pk_mul_f32 v[14:15], v[158:159], v[24:25] op_sel_hi:[1,0]
	v_cvt_f32_i32_e32 v13, v13
	v_pk_mul_f32 v[10:11], v[10:11], v[14:15]
	v_pk_mul_f32 v[14:15], v[156:157], v[18:19] op_sel_hi:[1,0]
	v_cvt_f32_i32_e32 v12, v12
	v_pk_mul_f32 v[14:15], v[14:15], v[16:17]
	v_exp_f32_e32 v22, v22
	v_exp_f32_e32 v14, v14
	v_exp_f32_e32 v15, v15
	v_exp_f32_e32 v23, v23
	v_cvt_f32_i32_e32 v7, v7
	v_cvt_f32_i32_e32 v6, v6
	v_pk_add_f32 v[14:15], v[14:15], 1.0 op_sel_hi:[1,0]
	v_pk_mul_f32 v[12:13], v[16:17], v[12:13]
	v_rcp_f32_e32 v14, v14
	v_rcp_f32_e32 v15, v15
	v_pk_mul_f32 v[16:17], v[154:155], v[24:25] op_sel_hi:[1,0]
	v_pk_add_f32 v[22:23], v[22:23], 1.0 op_sel_hi:[1,0]
	v_pk_mul_f32 v[12:13], v[12:13], v[16:17]
	v_rcp_f32_e32 v22, v22
	v_pk_mul_f32 v[12:13], v[12:13], v[14:15]
	v_pk_mul_f32 v[14:15], v[152:153], v[18:19] op_sel_hi:[1,0]
	v_rcp_f32_e32 v23, v23
	v_pk_mul_f32 v[14:15], v[14:15], v[6:7]
	v_cvt_f32_i32_e32 v3, v3
	v_exp_f32_e32 v14, v14
	v_exp_f32_e32 v15, v15
	v_cvt_f32_i32_e32 v2, v2
	v_cvt_f32_i32_e32 v9, v9
	v_cvt_f32_i32_e32 v8, v8
	v_pk_mul_f32 v[10:11], v[10:11], v[22:23]
	v_pk_mul_f32 v[2:3], v[6:7], v[2:3]
	v_cvt_pk_bf16_f32 v10, v10, v11
	v_cvt_pk_bf16_f32 v11, v12, v13
	v_pk_add_f32 v[12:13], v[14:15], 1.0 op_sel_hi:[1,0]
	v_pk_mul_f32 v[6:7], v[150:151], v[24:25] op_sel_hi:[1,0]
	v_rcp_f32_e32 v12, v12
	v_rcp_f32_e32 v13, v13
	v_pk_mul_f32 v[2:3], v[2:3], v[6:7]
	v_pk_mul_f32 v[6:7], v[148:149], v[18:19] op_sel_hi:[1,0]
	v_mad_i64_i32 v[20:21], s[28:29], v19, s49, v[162:163]
	v_pk_mul_f32 v[6:7], v[6:7], v[8:9]
	v_pk_mul_f32 v[2:3], v[2:3], v[12:13]
	v_exp_f32_e32 v6, v6
	v_exp_f32_e32 v7, v7
	v_cvt_pk_bf16_f32 v12, v2, v3
	v_cvt_f32_i32_e32 v3, v5
	v_cvt_f32_i32_e32 v2, v4
	v_pk_add_f32 v[4:5], v[6:7], 1.0 op_sel_hi:[1,0]
	v_pk_mul_f32 v[6:7], v[146:147], v[24:25] op_sel_hi:[1,0]
	v_rcp_f32_e32 v4, v4
	v_rcp_f32_e32 v5, v5
	v_pk_mul_f32 v[2:3], v[8:9], v[2:3]
	s_andn2_b64 vcc, exec, s[4:5]
	v_pk_mul_f32 v[2:3], v[2:3], v[6:7]
	s_mov_b64 s[4:5], -1
	v_pk_mul_f32 v[2:3], v[2:3], v[4:5]
	s_nop 0
	v_cvt_pk_bf16_f32 v13, v2, v3
	v_lshl_add_u64 v[2:3], v[20:21], 0, v[114:115]
	global_store_dwordx4 v[2:3], v[10:13], off sc1 nt
	s_cbranch_vccnz .LBB0_733
	s_andn2_b64 vcc, exec, s[12:13]
	s_cbranch_vccnz .LBB0_732
	s_barrier
	s_branch .LBB0_732

.LBB0_1598:
	s_lshl_b32 s21, s63, 11
	s_add_i32 s21, s21, 0
	s_add_i32 s23, s21, 0x20180
	s_lshl_b32 s21, s47, 2
	s_add_i32 s21, s23, s21
	v_lshl_add_u32 v154, v164, 2, s21
	ds_read_b128 v[146:149], v154 offset:1024
	ds_read_b128 v[150:153], v154 offset:1536
	ds_read_b128 v[182:185], v154 offset:1040
	ds_read_b128 v[186:189], v154 offset:1552
	v_cvt_f32_i32_e32 v127, v127
	v_cvt_f32_i32_e32 v126, v126
	s_waitcnt lgkmcnt(0)
	v_pk_mul_f32 v[154:155], v[148:149], v[152:153]
	v_pk_mul_f32 v[158:159], v[146:147], v[150:151]
	v_pk_mul_f32 v[152:153], v[182:183], s[16:17] op_sel_hi:[1,0]
	v_pk_mul_f32 v[150:151], v[182:183], v[186:187]
	v_lshl_add_u32 v182, v165, 2, s23
	ds_read_b32 v186, v182
	v_cvt_f32_i32_e32 v123, v123
	v_cvt_f32_i32_e32 v122, v122
	v_pk_mul_f32 v[160:161], v[146:147], s[16:17] op_sel_hi:[1,0]
	v_cvt_f32_i32_e32 v129, v129
	v_cvt_f32_i32_e32 v128, v128
	s_waitcnt lgkmcnt(0)
	v_pk_mul_f32 v[190:191], v[160:161], v[186:187] op_sel_hi:[1,0]
	v_mul_f32_e32 v192, v186, v186
	v_pk_mul_f32 v[156:157], v[148:149], s[16:17] op_sel_hi:[1,0]
	v_pk_mul_f32 v[190:191], v[190:191], v[126:127]
	v_pk_mul_f32 v[122:123], v[126:127], v[122:123]
	v_pk_mul_f32 v[126:127], v[158:159], v[192:193] op_sel_hi:[1,0]
	v_cvt_f32_i32_e32 v125, v125
	v_pk_mul_f32 v[122:123], v[122:123], v[126:127]
	v_pk_mul_f32 v[126:127], v[156:157], v[186:187] op_sel_hi:[1,0]
	v_cvt_f32_i32_e32 v124, v124
	v_pk_mul_f32 v[126:127], v[126:127], v[128:129]
	v_exp_f32_e32 v190, v190
	v_exp_f32_e32 v126, v126
	v_exp_f32_e32 v127, v127
	v_exp_f32_e32 v191, v191
	v_cvt_f32_i32_e32 v119, v119
	v_cvt_f32_i32_e32 v118, v118
	v_pk_add_f32 v[126:127], v[126:127], 1.0 op_sel_hi:[1,0]
	v_pk_mul_f32 v[124:125], v[128:129], v[124:125]
	v_rcp_f32_e32 v126, v126
	v_rcp_f32_e32 v127, v127
	v_pk_mul_f32 v[128:129], v[154:155], v[192:193] op_sel_hi:[1,0]
	v_pk_add_f32 v[190:191], v[190:191], 1.0 op_sel_hi:[1,0]
	v_pk_mul_f32 v[124:125], v[124:125], v[128:129]
	v_rcp_f32_e32 v190, v190
	v_pk_mul_f32 v[124:125], v[124:125], v[126:127]
	v_pk_mul_f32 v[126:127], v[152:153], v[186:187] op_sel_hi:[1,0]
	v_rcp_f32_e32 v191, v191
	v_pk_mul_f32 v[126:127], v[126:127], v[118:119]
	v_cvt_f32_i32_e32 v115, v115
	v_exp_f32_e32 v126, v126
	v_exp_f32_e32 v127, v127
	v_cvt_f32_i32_e32 v114, v114
	v_cvt_f32_i32_e32 v121, v121
	v_cvt_f32_i32_e32 v120, v120
	v_pk_mul_f32 v[122:123], v[122:123], v[190:191]
	v_pk_mul_f32 v[148:149], v[184:185], s[16:17] op_sel_hi:[1,0]
	v_cvt_pk_bf16_f32 v122, v122, v123
	v_cvt_pk_bf16_f32 v123, v124, v125
	v_pk_add_f32 v[124:125], v[126:127], 1.0 op_sel_hi:[1,0]
	v_pk_mul_f32 v[114:115], v[118:119], v[114:115]
	v_pk_mul_f32 v[118:119], v[150:151], v[192:193] op_sel_hi:[1,0]
	v_rcp_f32_e32 v124, v124
	v_rcp_f32_e32 v125, v125
	v_pk_mul_f32 v[114:115], v[114:115], v[118:119]
	v_pk_mul_f32 v[118:119], v[148:149], v[186:187] op_sel_hi:[1,0]
	v_pk_mul_f32 v[146:147], v[184:185], v[188:189]
	v_pk_mul_f32 v[118:119], v[118:119], v[120:121]
	v_pk_mul_f32 v[114:115], v[114:115], v[124:125]
	v_exp_f32_e32 v118, v118
	v_exp_f32_e32 v119, v119
	v_cvt_pk_bf16_f32 v124, v114, v115
	v_cvt_f32_i32_e32 v115, v117
	v_cvt_f32_i32_e32 v114, v116
	v_pk_add_f32 v[116:117], v[118:119], 1.0 op_sel_hi:[1,0]
	v_pk_mul_f32 v[118:119], v[146:147], v[192:193] op_sel_hi:[1,0]
	v_rcp_f32_e32 v116, v116
	v_rcp_f32_e32 v117, v117
	v_pk_mul_f32 v[114:115], v[120:121], v[114:115]
	v_lshl_or_b32 v184, s53, 7, v177
	s_lshl_b32 s21, s28, 8
	v_pk_mul_f32 v[114:115], v[114:115], v[118:119]
	v_ashrrev_i32_e32 v185, 31, v184
	v_add_u32_e32 v183, s21, v165
	v_mov_b64_e32 v[162:163], s[60:61]
	v_pk_mul_f32 v[114:115], v[114:115], v[116:117]
	v_mad_i64_i32 v[188:189], s[30:31], v183, s51, v[162:163]
	v_cvt_pk_bf16_f32 v125, v114, v115
	v_lshlrev_b64 v[114:115], 1, v[184:185]
	v_lshl_add_u64 v[116:117], v[188:189], 0, v[114:115]
	global_store_dwordx4 v[116:117], v[122:125], off sc1 nt
	ds_read_b32 v116, v182 offset:64
	v_cvt_f32_i32_e32 v111, v111
	v_cvt_f32_i32_e32 v110, v110
	v_cvt_f32_i32_e32 v107, v107
	v_cvt_f32_i32_e32 v106, v106
	v_add_u32_e32 v117, s21, v170
	v_cvt_f32_i32_e32 v113, v113
	v_cvt_f32_i32_e32 v112, v112
	s_waitcnt lgkmcnt(0)
	v_pk_mul_f32 v[120:121], v[160:161], v[116:117] op_sel_hi:[1,0]
	v_mul_f32_e32 v122, v116, v116
	v_pk_mul_f32 v[120:121], v[120:121], v[110:111]
	v_pk_mul_f32 v[106:107], v[110:111], v[106:107]
	v_pk_mul_f32 v[110:111], v[158:159], v[122:123] op_sel_hi:[1,0]
	v_cvt_f32_i32_e32 v109, v109
	v_pk_mul_f32 v[106:107], v[106:107], v[110:111]
	v_pk_mul_f32 v[110:111], v[156:157], v[116:117] op_sel_hi:[1,0]
	v_cvt_f32_i32_e32 v108, v108
	v_pk_mul_f32 v[110:111], v[110:111], v[112:113]
	v_exp_f32_e32 v120, v120
	v_exp_f32_e32 v110, v110
	v_exp_f32_e32 v111, v111
	v_exp_f32_e32 v121, v121
	v_cvt_f32_i32_e32 v103, v103
	v_cvt_f32_i32_e32 v102, v102
	v_pk_add_f32 v[110:111], v[110:111], 1.0 op_sel_hi:[1,0]
	v_pk_mul_f32 v[108:109], v[112:113], v[108:109]
	v_rcp_f32_e32 v110, v110
	v_rcp_f32_e32 v111, v111
	v_pk_mul_f32 v[112:113], v[154:155], v[122:123] op_sel_hi:[1,0]
	v_pk_add_f32 v[120:121], v[120:121], 1.0 op_sel_hi:[1,0]
	v_pk_mul_f32 v[108:109], v[108:109], v[112:113]
	v_rcp_f32_e32 v120, v120
	v_pk_mul_f32 v[108:109], v[108:109], v[110:111]
	v_pk_mul_f32 v[110:111], v[152:153], v[116:117] op_sel_hi:[1,0]
	v_rcp_f32_e32 v121, v121
	v_pk_mul_f32 v[110:111], v[110:111], v[102:103]
	v_cvt_f32_i32_e32 v99, v99
	v_exp_f32_e32 v110, v110
	v_exp_f32_e32 v111, v111
	v_cvt_f32_i32_e32 v98, v98
	v_cvt_f32_i32_e32 v105, v105
	v_cvt_f32_i32_e32 v104, v104
	v_pk_mul_f32 v[106:107], v[106:107], v[120:121]
	v_pk_mul_f32 v[98:99], v[102:103], v[98:99]
	v_cvt_pk_bf16_f32 v106, v106, v107
	v_cvt_pk_bf16_f32 v107, v108, v109
	v_pk_add_f32 v[108:109], v[110:111], 1.0 op_sel_hi:[1,0]
	v_pk_mul_f32 v[102:103], v[150:151], v[122:123] op_sel_hi:[1,0]
	v_rcp_f32_e32 v108, v108
	v_rcp_f32_e32 v109, v109
	v_pk_mul_f32 v[98:99], v[98:99], v[102:103]
	v_pk_mul_f32 v[102:103], v[148:149], v[116:117] op_sel_hi:[1,0]
	v_mad_i64_i32 v[118:119], s[30:31], v117, s51, v[162:163]
	v_pk_mul_f32 v[102:103], v[102:103], v[104:105]
	v_pk_mul_f32 v[98:99], v[98:99], v[108:109]
	v_exp_f32_e32 v102, v102
	v_exp_f32_e32 v103, v103
	v_cvt_pk_bf16_f32 v108, v98, v99
	v_cvt_f32_i32_e32 v99, v101
	v_cvt_f32_i32_e32 v98, v100
	v_pk_add_f32 v[100:101], v[102:103], 1.0 op_sel_hi:[1,0]
	v_pk_mul_f32 v[102:103], v[146:147], v[122:123] op_sel_hi:[1,0]
	v_rcp_f32_e32 v100, v100
	v_rcp_f32_e32 v101, v101
	v_pk_mul_f32 v[98:99], v[104:105], v[98:99]
	v_cvt_f32_i32_e32 v95, v95
	v_pk_mul_f32 v[98:99], v[98:99], v[102:103]
	v_cvt_f32_i32_e32 v94, v94
	v_pk_mul_f32 v[98:99], v[98:99], v[100:101]
	v_cvt_f32_i32_e32 v91, v91
	v_cvt_pk_bf16_f32 v109, v98, v99
	v_lshl_add_u64 v[98:99], v[118:119], 0, v[114:115]
	global_store_dwordx4 v[98:99], v[106:109], off sc1 nt
	ds_read_b32 v98, v182 offset:128
	v_cvt_f32_i32_e32 v90, v90
	v_add_u32_e32 v99, s21, v171
	v_cvt_f32_i32_e32 v97, v97
	v_cvt_f32_i32_e32 v96, v96
	s_waitcnt lgkmcnt(0)
	v_pk_mul_f32 v[102:103], v[160:161], v[98:99] op_sel_hi:[1,0]
	v_mul_f32_e32 v104, v98, v98
	v_pk_mul_f32 v[102:103], v[102:103], v[94:95]
	v_pk_mul_f32 v[90:91], v[94:95], v[90:91]
	v_pk_mul_f32 v[94:95], v[158:159], v[104:105] op_sel_hi:[1,0]
	v_cvt_f32_i32_e32 v93, v93
	v_pk_mul_f32 v[90:91], v[90:91], v[94:95]
	v_pk_mul_f32 v[94:95], v[156:157], v[98:99] op_sel_hi:[1,0]
	v_cvt_f32_i32_e32 v92, v92
	v_pk_mul_f32 v[94:95], v[94:95], v[96:97]
	v_exp_f32_e32 v102, v102
	v_exp_f32_e32 v94, v94
	v_exp_f32_e32 v95, v95
	v_exp_f32_e32 v103, v103
	v_cvt_f32_i32_e32 v87, v87
	v_cvt_f32_i32_e32 v86, v86
	v_pk_add_f32 v[94:95], v[94:95], 1.0 op_sel_hi:[1,0]
	v_pk_mul_f32 v[92:93], v[96:97], v[92:93]
	v_rcp_f32_e32 v94, v94
	v_rcp_f32_e32 v95, v95
	v_pk_mul_f32 v[96:97], v[154:155], v[104:105] op_sel_hi:[1,0]
	v_pk_add_f32 v[102:103], v[102:103], 1.0 op_sel_hi:[1,0]
	v_pk_mul_f32 v[92:93], v[92:93], v[96:97]
	v_rcp_f32_e32 v102, v102
	v_pk_mul_f32 v[92:93], v[92:93], v[94:95]
	v_pk_mul_f32 v[94:95], v[152:153], v[98:99] op_sel_hi:[1,0]
	v_rcp_f32_e32 v103, v103
	v_pk_mul_f32 v[94:95], v[94:95], v[86:87]
	v_cvt_f32_i32_e32 v83, v83
	v_exp_f32_e32 v94, v94
	v_exp_f32_e32 v95, v95
	v_cvt_f32_i32_e32 v82, v82
	v_cvt_f32_i32_e32 v89, v89
	v_cvt_f32_i32_e32 v88, v88
	v_pk_mul_f32 v[90:91], v[90:91], v[102:103]
	v_pk_mul_f32 v[82:83], v[86:87], v[82:83]
	v_cvt_pk_bf16_f32 v90, v90, v91
	v_cvt_pk_bf16_f32 v91, v92, v93
	v_pk_add_f32 v[92:93], v[94:95], 1.0 op_sel_hi:[1,0]
	v_pk_mul_f32 v[86:87], v[150:151], v[104:105] op_sel_hi:[1,0]
	v_rcp_f32_e32 v92, v92
	v_rcp_f32_e32 v93, v93
	v_pk_mul_f32 v[82:83], v[82:83], v[86:87]
	v_pk_mul_f32 v[86:87], v[148:149], v[98:99] op_sel_hi:[1,0]
	v_mad_i64_i32 v[100:101], s[30:31], v99, s51, v[162:163]
	v_pk_mul_f32 v[86:87], v[86:87], v[88:89]
	v_pk_mul_f32 v[82:83], v[82:83], v[92:93]
	v_exp_f32_e32 v86, v86
	v_exp_f32_e32 v87, v87
	v_cvt_pk_bf16_f32 v92, v82, v83
	v_cvt_f32_i32_e32 v83, v85
	v_cvt_f32_i32_e32 v82, v84
	v_pk_add_f32 v[84:85], v[86:87], 1.0 op_sel_hi:[1,0]
	v_pk_mul_f32 v[86:87], v[146:147], v[104:105] op_sel_hi:[1,0]
	v_rcp_f32_e32 v84, v84
	v_rcp_f32_e32 v85, v85
	v_pk_mul_f32 v[82:83], v[88:89], v[82:83]
	v_cvt_f32_i32_e32 v79, v79
	v_pk_mul_f32 v[82:83], v[82:83], v[86:87]
	v_cvt_f32_i32_e32 v78, v78
	v_pk_mul_f32 v[82:83], v[82:83], v[84:85]
	v_cvt_f32_i32_e32 v75, v75
	v_cvt_pk_bf16_f32 v93, v82, v83
	v_lshl_add_u64 v[82:83], v[100:101], 0, v[114:115]
	global_store_dwordx4 v[82:83], v[90:93], off sc1 nt
	ds_read_b32 v82, v182 offset:192
	v_cvt_f32_i32_e32 v74, v74
	v_add_u32_e32 v83, s21, v172
	v_cvt_f32_i32_e32 v81, v81
	v_cvt_f32_i32_e32 v80, v80
	s_waitcnt lgkmcnt(0)
	v_pk_mul_f32 v[86:87], v[160:161], v[82:83] op_sel_hi:[1,0]
	v_mul_f32_e32 v88, v82, v82
	v_pk_mul_f32 v[86:87], v[86:87], v[78:79]
	v_pk_mul_f32 v[74:75], v[78:79], v[74:75]
	v_pk_mul_f32 v[78:79], v[158:159], v[88:89] op_sel_hi:[1,0]
	v_cvt_f32_i32_e32 v77, v77
	v_pk_mul_f32 v[74:75], v[74:75], v[78:79]
	v_pk_mul_f32 v[78:79], v[156:157], v[82:83] op_sel_hi:[1,0]
	v_cvt_f32_i32_e32 v76, v76
	v_pk_mul_f32 v[78:79], v[78:79], v[80:81]
	v_exp_f32_e32 v86, v86
	v_exp_f32_e32 v78, v78
	v_exp_f32_e32 v79, v79
	v_exp_f32_e32 v87, v87
	v_cvt_f32_i32_e32 v71, v71
	v_cvt_f32_i32_e32 v70, v70
	v_pk_add_f32 v[78:79], v[78:79], 1.0 op_sel_hi:[1,0]
	v_pk_mul_f32 v[76:77], v[80:81], v[76:77]
	v_rcp_f32_e32 v78, v78
	v_rcp_f32_e32 v79, v79
	v_pk_mul_f32 v[80:81], v[154:155], v[88:89] op_sel_hi:[1,0]
	v_pk_add_f32 v[86:87], v[86:87], 1.0 op_sel_hi:[1,0]
	v_pk_mul_f32 v[76:77], v[76:77], v[80:81]
	v_rcp_f32_e32 v86, v86
	v_pk_mul_f32 v[76:77], v[76:77], v[78:79]
	v_pk_mul_f32 v[78:79], v[152:153], v[82:83] op_sel_hi:[1,0]
	v_rcp_f32_e32 v87, v87
	v_pk_mul_f32 v[78:79], v[78:79], v[70:71]
	v_cvt_f32_i32_e32 v67, v67
	v_exp_f32_e32 v78, v78
	v_exp_f32_e32 v79, v79
	v_cvt_f32_i32_e32 v66, v66
	v_cvt_f32_i32_e32 v73, v73
	v_cvt_f32_i32_e32 v72, v72
	v_pk_mul_f32 v[74:75], v[74:75], v[86:87]
	v_pk_mul_f32 v[66:67], v[70:71], v[66:67]
	v_cvt_pk_bf16_f32 v74, v74, v75
	v_cvt_pk_bf16_f32 v75, v76, v77
	v_pk_add_f32 v[76:77], v[78:79], 1.0 op_sel_hi:[1,0]
	v_pk_mul_f32 v[70:71], v[150:151], v[88:89] op_sel_hi:[1,0]
	v_rcp_f32_e32 v76, v76
	v_rcp_f32_e32 v77, v77
	v_pk_mul_f32 v[66:67], v[66:67], v[70:71]
	v_pk_mul_f32 v[70:71], v[148:149], v[82:83] op_sel_hi:[1,0]
	v_mad_i64_i32 v[84:85], s[30:31], v83, s51, v[162:163]
	v_pk_mul_f32 v[70:71], v[70:71], v[72:73]
	v_pk_mul_f32 v[66:67], v[66:67], v[76:77]
	v_exp_f32_e32 v70, v70
	v_exp_f32_e32 v71, v71
	v_cvt_pk_bf16_f32 v76, v66, v67
	v_cvt_f32_i32_e32 v67, v69
	v_cvt_f32_i32_e32 v66, v68
	v_pk_add_f32 v[68:69], v[70:71], 1.0 op_sel_hi:[1,0]
	v_pk_mul_f32 v[70:71], v[146:147], v[88:89] op_sel_hi:[1,0]
	v_rcp_f32_e32 v68, v68
	v_rcp_f32_e32 v69, v69
	v_pk_mul_f32 v[66:67], v[72:73], v[66:67]
	v_cvt_f32_i32_e32 v63, v63
	v_pk_mul_f32 v[66:67], v[66:67], v[70:71]
	v_cvt_f32_i32_e32 v62, v62
	v_pk_mul_f32 v[66:67], v[66:67], v[68:69]
	v_cvt_f32_i32_e32 v59, v59
	v_cvt_pk_bf16_f32 v77, v66, v67
	v_lshl_add_u64 v[66:67], v[84:85], 0, v[114:115]
	global_store_dwordx4 v[66:67], v[74:77], off sc1 nt
	ds_read_b32 v66, v182 offset:512
	v_cvt_f32_i32_e32 v58, v58
	v_add_u32_e32 v67, s21, v173
	v_cvt_f32_i32_e32 v65, v65
	v_cvt_f32_i32_e32 v64, v64
	s_waitcnt lgkmcnt(0)
	v_pk_mul_f32 v[70:71], v[160:161], v[66:67] op_sel_hi:[1,0]
	v_mul_f32_e32 v72, v66, v66
	v_pk_mul_f32 v[70:71], v[70:71], v[62:63]
	v_pk_mul_f32 v[58:59], v[62:63], v[58:59]
	v_pk_mul_f32 v[62:63], v[158:159], v[72:73] op_sel_hi:[1,0]
	v_cvt_f32_i32_e32 v61, v61
	v_pk_mul_f32 v[58:59], v[58:59], v[62:63]
	v_pk_mul_f32 v[62:63], v[156:157], v[66:67] op_sel_hi:[1,0]
	v_cvt_f32_i32_e32 v60, v60
	v_pk_mul_f32 v[62:63], v[62:63], v[64:65]
	v_exp_f32_e32 v70, v70
	v_exp_f32_e32 v62, v62
	v_exp_f32_e32 v63, v63
	v_exp_f32_e32 v71, v71
	v_cvt_f32_i32_e32 v55, v55
	v_cvt_f32_i32_e32 v54, v54
	v_pk_add_f32 v[62:63], v[62:63], 1.0 op_sel_hi:[1,0]
	v_pk_mul_f32 v[60:61], v[64:65], v[60:61]
	v_rcp_f32_e32 v62, v62
	v_rcp_f32_e32 v63, v63
	v_pk_mul_f32 v[64:65], v[154:155], v[72:73] op_sel_hi:[1,0]
	v_pk_add_f32 v[70:71], v[70:71], 1.0 op_sel_hi:[1,0]
	v_pk_mul_f32 v[60:61], v[60:61], v[64:65]
	v_rcp_f32_e32 v70, v70
	v_pk_mul_f32 v[60:61], v[60:61], v[62:63]
	v_pk_mul_f32 v[62:63], v[152:153], v[66:67] op_sel_hi:[1,0]
	v_rcp_f32_e32 v71, v71
	v_pk_mul_f32 v[62:63], v[62:63], v[54:55]
	v_cvt_f32_i32_e32 v51, v51
	v_exp_f32_e32 v62, v62
	v_exp_f32_e32 v63, v63
	v_cvt_f32_i32_e32 v50, v50
	v_cvt_f32_i32_e32 v57, v57
	v_cvt_f32_i32_e32 v56, v56
	v_pk_mul_f32 v[58:59], v[58:59], v[70:71]
	v_pk_mul_f32 v[50:51], v[54:55], v[50:51]
	v_cvt_pk_bf16_f32 v58, v58, v59
	v_cvt_pk_bf16_f32 v59, v60, v61
	v_pk_add_f32 v[60:61], v[62:63], 1.0 op_sel_hi:[1,0]
	v_pk_mul_f32 v[54:55], v[150:151], v[72:73] op_sel_hi:[1,0]
	v_rcp_f32_e32 v60, v60
	v_rcp_f32_e32 v61, v61
	v_pk_mul_f32 v[50:51], v[50:51], v[54:55]
	v_pk_mul_f32 v[54:55], v[148:149], v[66:67] op_sel_hi:[1,0]
	v_mad_i64_i32 v[68:69], s[30:31], v67, s51, v[162:163]
	v_pk_mul_f32 v[54:55], v[54:55], v[56:57]
	v_pk_mul_f32 v[50:51], v[50:51], v[60:61]
	v_exp_f32_e32 v54, v54
	v_exp_f32_e32 v55, v55
	v_cvt_pk_bf16_f32 v60, v50, v51
	v_cvt_f32_i32_e32 v51, v53
	v_cvt_f32_i32_e32 v50, v52
	v_pk_add_f32 v[52:53], v[54:55], 1.0 op_sel_hi:[1,0]
	v_pk_mul_f32 v[54:55], v[146:147], v[72:73] op_sel_hi:[1,0]
	v_rcp_f32_e32 v52, v52
	v_rcp_f32_e32 v53, v53
	v_pk_mul_f32 v[50:51], v[56:57], v[50:51]
	v_cvt_f32_i32_e32 v47, v47
	v_pk_mul_f32 v[50:51], v[50:51], v[54:55]
	v_cvt_f32_i32_e32 v46, v46
	v_pk_mul_f32 v[50:51], v[50:51], v[52:53]
	v_cvt_f32_i32_e32 v43, v43
	v_cvt_pk_bf16_f32 v61, v50, v51
	v_lshl_add_u64 v[50:51], v[68:69], 0, v[114:115]
	global_store_dwordx4 v[50:51], v[58:61], off sc1 nt
	ds_read_b32 v50, v182 offset:576
	v_cvt_f32_i32_e32 v42, v42
	v_add_u32_e32 v51, s21, v174
	v_cvt_f32_i32_e32 v49, v49
	v_cvt_f32_i32_e32 v48, v48
	s_waitcnt lgkmcnt(0)
	v_pk_mul_f32 v[54:55], v[160:161], v[50:51] op_sel_hi:[1,0]
	v_mul_f32_e32 v56, v50, v50
	v_pk_mul_f32 v[54:55], v[54:55], v[46:47]
	v_pk_mul_f32 v[42:43], v[46:47], v[42:43]
	v_pk_mul_f32 v[46:47], v[158:159], v[56:57] op_sel_hi:[1,0]
	v_cvt_f32_i32_e32 v45, v45
	v_pk_mul_f32 v[42:43], v[42:43], v[46:47]
	v_pk_mul_f32 v[46:47], v[156:157], v[50:51] op_sel_hi:[1,0]
	v_cvt_f32_i32_e32 v44, v44
	v_pk_mul_f32 v[46:47], v[46:47], v[48:49]
	v_exp_f32_e32 v54, v54
	v_exp_f32_e32 v46, v46
	v_exp_f32_e32 v47, v47
	v_exp_f32_e32 v55, v55
	v_cvt_f32_i32_e32 v39, v39
	v_cvt_f32_i32_e32 v38, v38
	v_pk_add_f32 v[46:47], v[46:47], 1.0 op_sel_hi:[1,0]
	v_pk_mul_f32 v[44:45], v[48:49], v[44:45]
	v_rcp_f32_e32 v46, v46
	v_rcp_f32_e32 v47, v47
	v_pk_mul_f32 v[48:49], v[154:155], v[56:57] op_sel_hi:[1,0]
	v_pk_add_f32 v[54:55], v[54:55], 1.0 op_sel_hi:[1,0]
	v_pk_mul_f32 v[44:45], v[44:45], v[48:49]
	v_rcp_f32_e32 v54, v54
	v_pk_mul_f32 v[44:45], v[44:45], v[46:47]
	v_pk_mul_f32 v[46:47], v[152:153], v[50:51] op_sel_hi:[1,0]
	v_rcp_f32_e32 v55, v55
	v_pk_mul_f32 v[46:47], v[46:47], v[38:39]
	v_cvt_f32_i32_e32 v35, v35
	v_exp_f32_e32 v46, v46
	v_exp_f32_e32 v47, v47
	v_cvt_f32_i32_e32 v34, v34
	v_cvt_f32_i32_e32 v41, v41
	v_cvt_f32_i32_e32 v40, v40
	v_pk_mul_f32 v[42:43], v[42:43], v[54:55]
	v_pk_mul_f32 v[34:35], v[38:39], v[34:35]
	v_cvt_pk_bf16_f32 v42, v42, v43
	v_cvt_pk_bf16_f32 v43, v44, v45
	v_pk_add_f32 v[44:45], v[46:47], 1.0 op_sel_hi:[1,0]
	v_pk_mul_f32 v[38:39], v[150:151], v[56:57] op_sel_hi:[1,0]
	v_rcp_f32_e32 v44, v44
	v_rcp_f32_e32 v45, v45
	v_pk_mul_f32 v[34:35], v[34:35], v[38:39]
	v_pk_mul_f32 v[38:39], v[148:149], v[50:51] op_sel_hi:[1,0]
	v_mad_i64_i32 v[52:53], s[30:31], v51, s51, v[162:163]
	v_pk_mul_f32 v[38:39], v[38:39], v[40:41]
	v_pk_mul_f32 v[34:35], v[34:35], v[44:45]
	v_exp_f32_e32 v38, v38
	v_exp_f32_e32 v39, v39
	v_cvt_pk_bf16_f32 v44, v34, v35
	v_cvt_f32_i32_e32 v35, v37
	v_cvt_f32_i32_e32 v34, v36
	v_pk_add_f32 v[36:37], v[38:39], 1.0 op_sel_hi:[1,0]
	v_pk_mul_f32 v[38:39], v[146:147], v[56:57] op_sel_hi:[1,0]
	v_rcp_f32_e32 v36, v36
	v_rcp_f32_e32 v37, v37
	v_pk_mul_f32 v[34:35], v[40:41], v[34:35]
	v_cvt_f32_i32_e32 v31, v31
	v_pk_mul_f32 v[34:35], v[34:35], v[38:39]
	v_cvt_f32_i32_e32 v30, v30
	v_pk_mul_f32 v[34:35], v[34:35], v[36:37]
	v_cvt_f32_i32_e32 v27, v27
	v_cvt_pk_bf16_f32 v45, v34, v35
	v_lshl_add_u64 v[34:35], v[52:53], 0, v[114:115]
	global_store_dwordx4 v[34:35], v[42:45], off sc1 nt
	ds_read_b32 v34, v182 offset:640
	v_cvt_f32_i32_e32 v26, v26
	v_add_u32_e32 v35, s21, v175
	v_cvt_f32_i32_e32 v33, v33
	v_cvt_f32_i32_e32 v32, v32
	s_waitcnt lgkmcnt(0)
	v_pk_mul_f32 v[38:39], v[160:161], v[34:35] op_sel_hi:[1,0]
	v_mul_f32_e32 v40, v34, v34
	v_pk_mul_f32 v[38:39], v[38:39], v[30:31]
	v_pk_mul_f32 v[26:27], v[30:31], v[26:27]
	v_pk_mul_f32 v[30:31], v[158:159], v[40:41] op_sel_hi:[1,0]
	v_cvt_f32_i32_e32 v29, v29
	v_pk_mul_f32 v[26:27], v[26:27], v[30:31]
	v_pk_mul_f32 v[30:31], v[156:157], v[34:35] op_sel_hi:[1,0]
	v_cvt_f32_i32_e32 v28, v28
	v_pk_mul_f32 v[30:31], v[30:31], v[32:33]
	v_exp_f32_e32 v38, v38
	v_exp_f32_e32 v30, v30
	v_exp_f32_e32 v31, v31
	v_exp_f32_e32 v39, v39
	v_cvt_f32_i32_e32 v23, v23
	v_cvt_f32_i32_e32 v22, v22
	v_pk_add_f32 v[30:31], v[30:31], 1.0 op_sel_hi:[1,0]
	v_pk_mul_f32 v[28:29], v[32:33], v[28:29]
	v_rcp_f32_e32 v30, v30
	v_rcp_f32_e32 v31, v31
	v_pk_mul_f32 v[32:33], v[154:155], v[40:41] op_sel_hi:[1,0]
	v_pk_add_f32 v[38:39], v[38:39], 1.0 op_sel_hi:[1,0]
	v_pk_mul_f32 v[28:29], v[28:29], v[32:33]
	v_rcp_f32_e32 v38, v38
	v_pk_mul_f32 v[28:29], v[28:29], v[30:31]
	v_pk_mul_f32 v[30:31], v[152:153], v[34:35] op_sel_hi:[1,0]
	v_rcp_f32_e32 v39, v39
	v_pk_mul_f32 v[30:31], v[30:31], v[22:23]
	v_cvt_f32_i32_e32 v19, v19
	v_exp_f32_e32 v30, v30
	v_exp_f32_e32 v31, v31
	v_cvt_f32_i32_e32 v18, v18
	v_cvt_f32_i32_e32 v25, v25
	v_cvt_f32_i32_e32 v24, v24
	v_pk_mul_f32 v[26:27], v[26:27], v[38:39]
	v_pk_mul_f32 v[18:19], v[22:23], v[18:19]
	v_cvt_pk_bf16_f32 v26, v26, v27
	v_cvt_pk_bf16_f32 v27, v28, v29
	v_pk_add_f32 v[28:29], v[30:31], 1.0 op_sel_hi:[1,0]
	v_pk_mul_f32 v[22:23], v[150:151], v[40:41] op_sel_hi:[1,0]
	v_rcp_f32_e32 v28, v28
	v_rcp_f32_e32 v29, v29
	v_pk_mul_f32 v[18:19], v[18:19], v[22:23]
	v_pk_mul_f32 v[22:23], v[148:149], v[34:35] op_sel_hi:[1,0]
	v_mad_i64_i32 v[36:37], s[30:31], v35, s51, v[162:163]
	v_pk_mul_f32 v[22:23], v[22:23], v[24:25]
	v_pk_mul_f32 v[18:19], v[18:19], v[28:29]
	v_exp_f32_e32 v22, v22
	v_exp_f32_e32 v23, v23
	v_cvt_pk_bf16_f32 v28, v18, v19
	v_cvt_f32_i32_e32 v19, v21
	v_cvt_f32_i32_e32 v18, v20
	v_pk_add_f32 v[20:21], v[22:23], 1.0 op_sel_hi:[1,0]
	v_pk_mul_f32 v[22:23], v[146:147], v[40:41] op_sel_hi:[1,0]
	v_rcp_f32_e32 v20, v20
	v_rcp_f32_e32 v21, v21
	v_pk_mul_f32 v[18:19], v[24:25], v[18:19]
	v_cvt_f32_i32_e32 v15, v15
	v_pk_mul_f32 v[18:19], v[18:19], v[22:23]
	v_cvt_f32_i32_e32 v14, v14
	v_pk_mul_f32 v[18:19], v[18:19], v[20:21]
	v_cvt_f32_i32_e32 v11, v11
	v_cvt_pk_bf16_f32 v29, v18, v19
	v_lshl_add_u64 v[18:19], v[36:37], 0, v[114:115]
	global_store_dwordx4 v[18:19], v[26:29], off sc1 nt
	ds_read_b32 v18, v182 offset:704
	v_cvt_f32_i32_e32 v10, v10
	v_add_u32_e32 v19, s21, v176
	v_cvt_f32_i32_e32 v17, v17
	v_cvt_f32_i32_e32 v16, v16
	s_waitcnt lgkmcnt(0)
	v_pk_mul_f32 v[22:23], v[160:161], v[18:19] op_sel_hi:[1,0]
	v_mul_f32_e32 v24, v18, v18
	v_pk_mul_f32 v[22:23], v[22:23], v[14:15]
	v_pk_mul_f32 v[10:11], v[14:15], v[10:11]
	v_pk_mul_f32 v[14:15], v[158:159], v[24:25] op_sel_hi:[1,0]
	v_cvt_f32_i32_e32 v13, v13
	v_pk_mul_f32 v[10:11], v[10:11], v[14:15]
	v_pk_mul_f32 v[14:15], v[156:157], v[18:19] op_sel_hi:[1,0]
	v_cvt_f32_i32_e32 v12, v12
	v_pk_mul_f32 v[14:15], v[14:15], v[16:17]
	v_exp_f32_e32 v22, v22
	v_exp_f32_e32 v14, v14
	v_exp_f32_e32 v15, v15
	v_exp_f32_e32 v23, v23
	v_cvt_f32_i32_e32 v7, v7
	v_cvt_f32_i32_e32 v6, v6
	v_pk_add_f32 v[14:15], v[14:15], 1.0 op_sel_hi:[1,0]
	v_pk_mul_f32 v[12:13], v[16:17], v[12:13]
	v_rcp_f32_e32 v14, v14
	v_rcp_f32_e32 v15, v15
	v_pk_mul_f32 v[16:17], v[154:155], v[24:25] op_sel_hi:[1,0]
	v_pk_add_f32 v[22:23], v[22:23], 1.0 op_sel_hi:[1,0]
	v_pk_mul_f32 v[12:13], v[12:13], v[16:17]
	v_rcp_f32_e32 v22, v22
	v_pk_mul_f32 v[12:13], v[12:13], v[14:15]
	v_pk_mul_f32 v[14:15], v[152:153], v[18:19] op_sel_hi:[1,0]
	v_rcp_f32_e32 v23, v23
	v_pk_mul_f32 v[14:15], v[14:15], v[6:7]
	v_cvt_f32_i32_e32 v3, v3
	v_exp_f32_e32 v14, v14
	v_exp_f32_e32 v15, v15
	v_cvt_f32_i32_e32 v2, v2
	v_cvt_f32_i32_e32 v9, v9
	v_cvt_f32_i32_e32 v8, v8
	v_pk_mul_f32 v[10:11], v[10:11], v[22:23]
	v_pk_mul_f32 v[2:3], v[6:7], v[2:3]
	v_cvt_pk_bf16_f32 v10, v10, v11
	v_cvt_pk_bf16_f32 v11, v12, v13
	v_pk_add_f32 v[12:13], v[14:15], 1.0 op_sel_hi:[1,0]
	v_pk_mul_f32 v[6:7], v[150:151], v[24:25] op_sel_hi:[1,0]
	v_rcp_f32_e32 v12, v12
	v_rcp_f32_e32 v13, v13
	v_pk_mul_f32 v[2:3], v[2:3], v[6:7]
	v_pk_mul_f32 v[6:7], v[148:149], v[18:19] op_sel_hi:[1,0]
	v_mad_i64_i32 v[20:21], s[30:31], v19, s51, v[162:163]
	v_pk_mul_f32 v[6:7], v[6:7], v[8:9]
	v_pk_mul_f32 v[2:3], v[2:3], v[12:13]
	v_exp_f32_e32 v6, v6
	v_exp_f32_e32 v7, v7
	v_cvt_pk_bf16_f32 v12, v2, v3
	v_cvt_f32_i32_e32 v3, v5
	v_cvt_f32_i32_e32 v2, v4
	v_pk_add_f32 v[4:5], v[6:7], 1.0 op_sel_hi:[1,0]
	v_pk_mul_f32 v[6:7], v[146:147], v[24:25] op_sel_hi:[1,0]
	v_rcp_f32_e32 v4, v4
	v_rcp_f32_e32 v5, v5
	v_pk_mul_f32 v[2:3], v[8:9], v[2:3]
	s_andn2_b64 vcc, exec, s[4:5]
	v_pk_mul_f32 v[2:3], v[2:3], v[6:7]
	s_mov_b64 s[4:5], -1
	v_pk_mul_f32 v[2:3], v[2:3], v[4:5]
	s_nop 0
	v_cvt_pk_bf16_f32 v13, v2, v3
	v_lshl_add_u64 v[2:3], v[20:21], 0, v[114:115]
	global_store_dwordx4 v[2:3], v[10:13], off sc1 nt
	s_cbranch_vccnz .LBB0_1591
	s_andn2_b64 vcc, exec, s[12:13]
	s_cbranch_vccnz .LBB0_1590
	s_barrier
	s_branch .LBB0_1590

.LBB0_2473:
	s_lshl_b32 s17, s52, 11
	s_add_i32 s17, s17, 0
	s_add_i32 s21, s17, 0x20180
	s_lshl_b32 s17, s45, 2
	s_add_i32 s17, s21, s17
	v_lshl_add_u32 v154, v164, 2, s17
	ds_read_b128 v[146:149], v154 offset:1024
	ds_read_b128 v[150:153], v154 offset:1536
	ds_read_b128 v[182:185], v154 offset:1040
	ds_read_b128 v[186:189], v154 offset:1552
	v_cvt_f32_i32_e32 v127, v127
	v_cvt_f32_i32_e32 v126, v126
	s_waitcnt lgkmcnt(0)
	v_pk_mul_f32 v[154:155], v[148:149], v[152:153]
	v_pk_mul_f32 v[158:159], v[146:147], v[150:151]
	v_pk_mul_f32 v[152:153], v[182:183], s[14:15] op_sel_hi:[1,0]
	v_pk_mul_f32 v[150:151], v[182:183], v[186:187]
	v_lshl_add_u32 v182, v165, 2, s21
	ds_read_b32 v186, v182
	v_cvt_f32_i32_e32 v123, v123
	v_cvt_f32_i32_e32 v122, v122
	v_pk_mul_f32 v[160:161], v[146:147], s[14:15] op_sel_hi:[1,0]
	v_cvt_f32_i32_e32 v129, v129
	v_cvt_f32_i32_e32 v128, v128
	s_waitcnt lgkmcnt(0)
	v_pk_mul_f32 v[190:191], v[160:161], v[186:187] op_sel_hi:[1,0]
	v_mul_f32_e32 v192, v186, v186
	v_pk_mul_f32 v[156:157], v[148:149], s[14:15] op_sel_hi:[1,0]
	v_pk_mul_f32 v[190:191], v[190:191], v[126:127]
	v_pk_mul_f32 v[122:123], v[126:127], v[122:123]
	v_pk_mul_f32 v[126:127], v[158:159], v[192:193] op_sel_hi:[1,0]
	v_cvt_f32_i32_e32 v125, v125
	v_pk_mul_f32 v[122:123], v[122:123], v[126:127]
	v_pk_mul_f32 v[126:127], v[156:157], v[186:187] op_sel_hi:[1,0]
	v_cvt_f32_i32_e32 v124, v124
	v_pk_mul_f32 v[126:127], v[126:127], v[128:129]
	v_exp_f32_e32 v190, v190
	v_exp_f32_e32 v126, v126
	v_exp_f32_e32 v127, v127
	v_exp_f32_e32 v191, v191
	v_cvt_f32_i32_e32 v119, v119
	v_cvt_f32_i32_e32 v118, v118
	v_pk_add_f32 v[126:127], v[126:127], 1.0 op_sel_hi:[1,0]
	v_pk_mul_f32 v[124:125], v[128:129], v[124:125]
	v_rcp_f32_e32 v126, v126
	v_rcp_f32_e32 v127, v127
	v_pk_mul_f32 v[128:129], v[154:155], v[192:193] op_sel_hi:[1,0]
	v_pk_add_f32 v[190:191], v[190:191], 1.0 op_sel_hi:[1,0]
	v_pk_mul_f32 v[124:125], v[124:125], v[128:129]
	v_rcp_f32_e32 v190, v190
	v_pk_mul_f32 v[124:125], v[124:125], v[126:127]
	v_pk_mul_f32 v[126:127], v[152:153], v[186:187] op_sel_hi:[1,0]
	v_rcp_f32_e32 v191, v191
	v_pk_mul_f32 v[126:127], v[126:127], v[118:119]
	v_cvt_f32_i32_e32 v115, v115
	v_exp_f32_e32 v126, v126
	v_exp_f32_e32 v127, v127
	v_cvt_f32_i32_e32 v114, v114
	v_cvt_f32_i32_e32 v121, v121
	v_cvt_f32_i32_e32 v120, v120
	v_pk_mul_f32 v[122:123], v[122:123], v[190:191]
	v_pk_mul_f32 v[148:149], v[184:185], s[14:15] op_sel_hi:[1,0]
	v_cvt_pk_bf16_f32 v122, v122, v123
	v_cvt_pk_bf16_f32 v123, v124, v125
	v_pk_add_f32 v[124:125], v[126:127], 1.0 op_sel_hi:[1,0]
	v_pk_mul_f32 v[114:115], v[118:119], v[114:115]
	v_pk_mul_f32 v[118:119], v[150:151], v[192:193] op_sel_hi:[1,0]
	v_rcp_f32_e32 v124, v124
	v_rcp_f32_e32 v125, v125
	v_pk_mul_f32 v[114:115], v[114:115], v[118:119]
	v_pk_mul_f32 v[118:119], v[148:149], v[186:187] op_sel_hi:[1,0]
	v_pk_mul_f32 v[146:147], v[184:185], v[188:189]
	v_pk_mul_f32 v[118:119], v[118:119], v[120:121]
	v_pk_mul_f32 v[114:115], v[114:115], v[124:125]
	v_exp_f32_e32 v118, v118
	v_exp_f32_e32 v119, v119
	v_cvt_pk_bf16_f32 v124, v114, v115
	v_cvt_f32_i32_e32 v115, v117
	v_cvt_f32_i32_e32 v114, v116
	v_pk_add_f32 v[116:117], v[118:119], 1.0 op_sel_hi:[1,0]
	v_pk_mul_f32 v[118:119], v[146:147], v[192:193] op_sel_hi:[1,0]
	v_rcp_f32_e32 v116, v116
	v_rcp_f32_e32 v117, v117
	v_pk_mul_f32 v[114:115], v[120:121], v[114:115]
	v_lshl_or_b32 v184, s51, 7, v177
	s_lshl_b32 s17, s26, 8
	v_pk_mul_f32 v[114:115], v[114:115], v[118:119]
	v_ashrrev_i32_e32 v185, 31, v184
	v_add_u32_e32 v183, s17, v165
	v_mov_b64_e32 v[162:163], s[60:61]
	v_pk_mul_f32 v[114:115], v[114:115], v[116:117]
	v_mad_i64_i32 v[188:189], s[28:29], v183, s49, v[162:163]
	v_cvt_pk_bf16_f32 v125, v114, v115
	v_lshlrev_b64 v[114:115], 1, v[184:185]
	v_lshl_add_u64 v[116:117], v[188:189], 0, v[114:115]
	global_store_dwordx4 v[116:117], v[122:125], off sc1 nt
	ds_read_b32 v116, v182 offset:64
	v_cvt_f32_i32_e32 v111, v111
	v_cvt_f32_i32_e32 v110, v110
	v_cvt_f32_i32_e32 v107, v107
	v_cvt_f32_i32_e32 v106, v106
	v_add_u32_e32 v117, s17, v170
	v_cvt_f32_i32_e32 v113, v113
	v_cvt_f32_i32_e32 v112, v112
	s_waitcnt lgkmcnt(0)
	v_pk_mul_f32 v[120:121], v[160:161], v[116:117] op_sel_hi:[1,0]
	v_mul_f32_e32 v122, v116, v116
	v_pk_mul_f32 v[120:121], v[120:121], v[110:111]
	v_pk_mul_f32 v[106:107], v[110:111], v[106:107]
	v_pk_mul_f32 v[110:111], v[158:159], v[122:123] op_sel_hi:[1,0]
	v_cvt_f32_i32_e32 v109, v109
	v_pk_mul_f32 v[106:107], v[106:107], v[110:111]
	v_pk_mul_f32 v[110:111], v[156:157], v[116:117] op_sel_hi:[1,0]
	v_cvt_f32_i32_e32 v108, v108
	v_pk_mul_f32 v[110:111], v[110:111], v[112:113]
	v_exp_f32_e32 v120, v120
	v_exp_f32_e32 v110, v110
	v_exp_f32_e32 v111, v111
	v_exp_f32_e32 v121, v121
	v_cvt_f32_i32_e32 v103, v103
	v_cvt_f32_i32_e32 v102, v102
	v_pk_add_f32 v[110:111], v[110:111], 1.0 op_sel_hi:[1,0]
	v_pk_mul_f32 v[108:109], v[112:113], v[108:109]
	v_rcp_f32_e32 v110, v110
	v_rcp_f32_e32 v111, v111
	v_pk_mul_f32 v[112:113], v[154:155], v[122:123] op_sel_hi:[1,0]
	v_pk_add_f32 v[120:121], v[120:121], 1.0 op_sel_hi:[1,0]
	v_pk_mul_f32 v[108:109], v[108:109], v[112:113]
	v_rcp_f32_e32 v120, v120
	v_pk_mul_f32 v[108:109], v[108:109], v[110:111]
	v_pk_mul_f32 v[110:111], v[152:153], v[116:117] op_sel_hi:[1,0]
	v_rcp_f32_e32 v121, v121
	v_pk_mul_f32 v[110:111], v[110:111], v[102:103]
	v_cvt_f32_i32_e32 v99, v99
	v_exp_f32_e32 v110, v110
	v_exp_f32_e32 v111, v111
	v_cvt_f32_i32_e32 v98, v98
	v_cvt_f32_i32_e32 v105, v105
	v_cvt_f32_i32_e32 v104, v104
	v_pk_mul_f32 v[106:107], v[106:107], v[120:121]
	v_pk_mul_f32 v[98:99], v[102:103], v[98:99]
	v_cvt_pk_bf16_f32 v106, v106, v107
	v_cvt_pk_bf16_f32 v107, v108, v109
	v_pk_add_f32 v[108:109], v[110:111], 1.0 op_sel_hi:[1,0]
	v_pk_mul_f32 v[102:103], v[150:151], v[122:123] op_sel_hi:[1,0]
	v_rcp_f32_e32 v108, v108
	v_rcp_f32_e32 v109, v109
	v_pk_mul_f32 v[98:99], v[98:99], v[102:103]
	v_pk_mul_f32 v[102:103], v[148:149], v[116:117] op_sel_hi:[1,0]
	v_mad_i64_i32 v[118:119], s[28:29], v117, s49, v[162:163]
	v_pk_mul_f32 v[102:103], v[102:103], v[104:105]
	v_pk_mul_f32 v[98:99], v[98:99], v[108:109]
	v_exp_f32_e32 v102, v102
	v_exp_f32_e32 v103, v103
	v_cvt_pk_bf16_f32 v108, v98, v99
	v_cvt_f32_i32_e32 v99, v101
	v_cvt_f32_i32_e32 v98, v100
	v_pk_add_f32 v[100:101], v[102:103], 1.0 op_sel_hi:[1,0]
	v_pk_mul_f32 v[102:103], v[146:147], v[122:123] op_sel_hi:[1,0]
	v_rcp_f32_e32 v100, v100
	v_rcp_f32_e32 v101, v101
	v_pk_mul_f32 v[98:99], v[104:105], v[98:99]
	v_cvt_f32_i32_e32 v95, v95
	v_pk_mul_f32 v[98:99], v[98:99], v[102:103]
	v_cvt_f32_i32_e32 v94, v94
	v_pk_mul_f32 v[98:99], v[98:99], v[100:101]
	v_cvt_f32_i32_e32 v91, v91
	v_cvt_pk_bf16_f32 v109, v98, v99
	v_lshl_add_u64 v[98:99], v[118:119], 0, v[114:115]
	global_store_dwordx4 v[98:99], v[106:109], off sc1 nt
	ds_read_b32 v98, v182 offset:128
	v_cvt_f32_i32_e32 v90, v90
	v_add_u32_e32 v99, s17, v171
	v_cvt_f32_i32_e32 v97, v97
	v_cvt_f32_i32_e32 v96, v96
	s_waitcnt lgkmcnt(0)
	v_pk_mul_f32 v[102:103], v[160:161], v[98:99] op_sel_hi:[1,0]
	v_mul_f32_e32 v104, v98, v98
	v_pk_mul_f32 v[102:103], v[102:103], v[94:95]
	v_pk_mul_f32 v[90:91], v[94:95], v[90:91]
	v_pk_mul_f32 v[94:95], v[158:159], v[104:105] op_sel_hi:[1,0]
	v_cvt_f32_i32_e32 v93, v93
	v_pk_mul_f32 v[90:91], v[90:91], v[94:95]
	v_pk_mul_f32 v[94:95], v[156:157], v[98:99] op_sel_hi:[1,0]
	v_cvt_f32_i32_e32 v92, v92
	v_pk_mul_f32 v[94:95], v[94:95], v[96:97]
	v_exp_f32_e32 v102, v102
	v_exp_f32_e32 v94, v94
	v_exp_f32_e32 v95, v95
	v_exp_f32_e32 v103, v103
	v_cvt_f32_i32_e32 v87, v87
	v_cvt_f32_i32_e32 v86, v86
	v_pk_add_f32 v[94:95], v[94:95], 1.0 op_sel_hi:[1,0]
	v_pk_mul_f32 v[92:93], v[96:97], v[92:93]
	v_rcp_f32_e32 v94, v94
	v_rcp_f32_e32 v95, v95
	v_pk_mul_f32 v[96:97], v[154:155], v[104:105] op_sel_hi:[1,0]
	v_pk_add_f32 v[102:103], v[102:103], 1.0 op_sel_hi:[1,0]
	v_pk_mul_f32 v[92:93], v[92:93], v[96:97]
	v_rcp_f32_e32 v102, v102
	v_pk_mul_f32 v[92:93], v[92:93], v[94:95]
	v_pk_mul_f32 v[94:95], v[152:153], v[98:99] op_sel_hi:[1,0]
	v_rcp_f32_e32 v103, v103
	v_pk_mul_f32 v[94:95], v[94:95], v[86:87]
	v_cvt_f32_i32_e32 v83, v83
	v_exp_f32_e32 v94, v94
	v_exp_f32_e32 v95, v95
	v_cvt_f32_i32_e32 v82, v82
	v_cvt_f32_i32_e32 v89, v89
	v_cvt_f32_i32_e32 v88, v88
	v_pk_mul_f32 v[90:91], v[90:91], v[102:103]
	v_pk_mul_f32 v[82:83], v[86:87], v[82:83]
	v_cvt_pk_bf16_f32 v90, v90, v91
	v_cvt_pk_bf16_f32 v91, v92, v93
	v_pk_add_f32 v[92:93], v[94:95], 1.0 op_sel_hi:[1,0]
	v_pk_mul_f32 v[86:87], v[150:151], v[104:105] op_sel_hi:[1,0]
	v_rcp_f32_e32 v92, v92
	v_rcp_f32_e32 v93, v93
	v_pk_mul_f32 v[82:83], v[82:83], v[86:87]
	v_pk_mul_f32 v[86:87], v[148:149], v[98:99] op_sel_hi:[1,0]
	v_mad_i64_i32 v[100:101], s[28:29], v99, s49, v[162:163]
	v_pk_mul_f32 v[86:87], v[86:87], v[88:89]
	v_pk_mul_f32 v[82:83], v[82:83], v[92:93]
	v_exp_f32_e32 v86, v86
	v_exp_f32_e32 v87, v87
	v_cvt_pk_bf16_f32 v92, v82, v83
	v_cvt_f32_i32_e32 v83, v85
	v_cvt_f32_i32_e32 v82, v84
	v_pk_add_f32 v[84:85], v[86:87], 1.0 op_sel_hi:[1,0]
	v_pk_mul_f32 v[86:87], v[146:147], v[104:105] op_sel_hi:[1,0]
	v_rcp_f32_e32 v84, v84
	v_rcp_f32_e32 v85, v85
	v_pk_mul_f32 v[82:83], v[88:89], v[82:83]
	v_cvt_f32_i32_e32 v79, v79
	v_pk_mul_f32 v[82:83], v[82:83], v[86:87]
	v_cvt_f32_i32_e32 v78, v78
	v_pk_mul_f32 v[82:83], v[82:83], v[84:85]
	v_cvt_f32_i32_e32 v75, v75
	v_cvt_pk_bf16_f32 v93, v82, v83
	v_lshl_add_u64 v[82:83], v[100:101], 0, v[114:115]
	global_store_dwordx4 v[82:83], v[90:93], off sc1 nt
	ds_read_b32 v82, v182 offset:192
	v_cvt_f32_i32_e32 v74, v74
	v_add_u32_e32 v83, s17, v172
	v_cvt_f32_i32_e32 v81, v81
	v_cvt_f32_i32_e32 v80, v80
	s_waitcnt lgkmcnt(0)
	v_pk_mul_f32 v[86:87], v[160:161], v[82:83] op_sel_hi:[1,0]
	v_mul_f32_e32 v88, v82, v82
	v_pk_mul_f32 v[86:87], v[86:87], v[78:79]
	v_pk_mul_f32 v[74:75], v[78:79], v[74:75]
	v_pk_mul_f32 v[78:79], v[158:159], v[88:89] op_sel_hi:[1,0]
	v_cvt_f32_i32_e32 v77, v77
	v_pk_mul_f32 v[74:75], v[74:75], v[78:79]
	v_pk_mul_f32 v[78:79], v[156:157], v[82:83] op_sel_hi:[1,0]
	v_cvt_f32_i32_e32 v76, v76
	v_pk_mul_f32 v[78:79], v[78:79], v[80:81]
	v_exp_f32_e32 v86, v86
	v_exp_f32_e32 v78, v78
	v_exp_f32_e32 v79, v79
	v_exp_f32_e32 v87, v87
	v_cvt_f32_i32_e32 v71, v71
	v_cvt_f32_i32_e32 v70, v70
	v_pk_add_f32 v[78:79], v[78:79], 1.0 op_sel_hi:[1,0]
	v_pk_mul_f32 v[76:77], v[80:81], v[76:77]
	v_rcp_f32_e32 v78, v78
	v_rcp_f32_e32 v79, v79
	v_pk_mul_f32 v[80:81], v[154:155], v[88:89] op_sel_hi:[1,0]
	v_pk_add_f32 v[86:87], v[86:87], 1.0 op_sel_hi:[1,0]
	v_pk_mul_f32 v[76:77], v[76:77], v[80:81]
	v_rcp_f32_e32 v86, v86
	v_pk_mul_f32 v[76:77], v[76:77], v[78:79]
	v_pk_mul_f32 v[78:79], v[152:153], v[82:83] op_sel_hi:[1,0]
	v_rcp_f32_e32 v87, v87
	v_pk_mul_f32 v[78:79], v[78:79], v[70:71]
	v_cvt_f32_i32_e32 v67, v67
	v_exp_f32_e32 v78, v78
	v_exp_f32_e32 v79, v79
	v_cvt_f32_i32_e32 v66, v66
	v_cvt_f32_i32_e32 v73, v73
	v_cvt_f32_i32_e32 v72, v72
	v_pk_mul_f32 v[74:75], v[74:75], v[86:87]
	v_pk_mul_f32 v[66:67], v[70:71], v[66:67]
	v_cvt_pk_bf16_f32 v74, v74, v75
	v_cvt_pk_bf16_f32 v75, v76, v77
	v_pk_add_f32 v[76:77], v[78:79], 1.0 op_sel_hi:[1,0]
	v_pk_mul_f32 v[70:71], v[150:151], v[88:89] op_sel_hi:[1,0]
	v_rcp_f32_e32 v76, v76
	v_rcp_f32_e32 v77, v77
	v_pk_mul_f32 v[66:67], v[66:67], v[70:71]
	v_pk_mul_f32 v[70:71], v[148:149], v[82:83] op_sel_hi:[1,0]
	v_mad_i64_i32 v[84:85], s[28:29], v83, s49, v[162:163]
	v_pk_mul_f32 v[70:71], v[70:71], v[72:73]
	v_pk_mul_f32 v[66:67], v[66:67], v[76:77]
	v_exp_f32_e32 v70, v70
	v_exp_f32_e32 v71, v71
	v_cvt_pk_bf16_f32 v76, v66, v67
	v_cvt_f32_i32_e32 v67, v69
	v_cvt_f32_i32_e32 v66, v68
	v_pk_add_f32 v[68:69], v[70:71], 1.0 op_sel_hi:[1,0]
	v_pk_mul_f32 v[70:71], v[146:147], v[88:89] op_sel_hi:[1,0]
	v_rcp_f32_e32 v68, v68
	v_rcp_f32_e32 v69, v69
	v_pk_mul_f32 v[66:67], v[72:73], v[66:67]
	v_cvt_f32_i32_e32 v63, v63
	v_pk_mul_f32 v[66:67], v[66:67], v[70:71]
	v_cvt_f32_i32_e32 v62, v62
	v_pk_mul_f32 v[66:67], v[66:67], v[68:69]
	v_cvt_f32_i32_e32 v59, v59
	v_cvt_pk_bf16_f32 v77, v66, v67
	v_lshl_add_u64 v[66:67], v[84:85], 0, v[114:115]
	global_store_dwordx4 v[66:67], v[74:77], off sc1 nt
	ds_read_b32 v66, v182 offset:512
	v_cvt_f32_i32_e32 v58, v58
	v_add_u32_e32 v67, s17, v173
	v_cvt_f32_i32_e32 v65, v65
	v_cvt_f32_i32_e32 v64, v64
	s_waitcnt lgkmcnt(0)
	v_pk_mul_f32 v[70:71], v[160:161], v[66:67] op_sel_hi:[1,0]
	v_mul_f32_e32 v72, v66, v66
	v_pk_mul_f32 v[70:71], v[70:71], v[62:63]
	v_pk_mul_f32 v[58:59], v[62:63], v[58:59]
	v_pk_mul_f32 v[62:63], v[158:159], v[72:73] op_sel_hi:[1,0]
	v_cvt_f32_i32_e32 v61, v61
	v_pk_mul_f32 v[58:59], v[58:59], v[62:63]
	v_pk_mul_f32 v[62:63], v[156:157], v[66:67] op_sel_hi:[1,0]
	v_cvt_f32_i32_e32 v60, v60
	v_pk_mul_f32 v[62:63], v[62:63], v[64:65]
	v_exp_f32_e32 v70, v70
	v_exp_f32_e32 v62, v62
	v_exp_f32_e32 v63, v63
	v_exp_f32_e32 v71, v71
	v_cvt_f32_i32_e32 v55, v55
	v_cvt_f32_i32_e32 v54, v54
	v_pk_add_f32 v[62:63], v[62:63], 1.0 op_sel_hi:[1,0]
	v_pk_mul_f32 v[60:61], v[64:65], v[60:61]
	v_rcp_f32_e32 v62, v62
	v_rcp_f32_e32 v63, v63
	v_pk_mul_f32 v[64:65], v[154:155], v[72:73] op_sel_hi:[1,0]
	v_pk_add_f32 v[70:71], v[70:71], 1.0 op_sel_hi:[1,0]
	v_pk_mul_f32 v[60:61], v[60:61], v[64:65]
	v_rcp_f32_e32 v70, v70
	v_pk_mul_f32 v[60:61], v[60:61], v[62:63]
	v_pk_mul_f32 v[62:63], v[152:153], v[66:67] op_sel_hi:[1,0]
	v_rcp_f32_e32 v71, v71
	v_pk_mul_f32 v[62:63], v[62:63], v[54:55]
	v_cvt_f32_i32_e32 v51, v51
	v_exp_f32_e32 v62, v62
	v_exp_f32_e32 v63, v63
	v_cvt_f32_i32_e32 v50, v50
	v_cvt_f32_i32_e32 v57, v57
	v_cvt_f32_i32_e32 v56, v56
	v_pk_mul_f32 v[58:59], v[58:59], v[70:71]
	v_pk_mul_f32 v[50:51], v[54:55], v[50:51]
	v_cvt_pk_bf16_f32 v58, v58, v59
	v_cvt_pk_bf16_f32 v59, v60, v61
	v_pk_add_f32 v[60:61], v[62:63], 1.0 op_sel_hi:[1,0]
	v_pk_mul_f32 v[54:55], v[150:151], v[72:73] op_sel_hi:[1,0]
	v_rcp_f32_e32 v60, v60
	v_rcp_f32_e32 v61, v61
	v_pk_mul_f32 v[50:51], v[50:51], v[54:55]
	v_pk_mul_f32 v[54:55], v[148:149], v[66:67] op_sel_hi:[1,0]
	v_mad_i64_i32 v[68:69], s[28:29], v67, s49, v[162:163]
	v_pk_mul_f32 v[54:55], v[54:55], v[56:57]
	v_pk_mul_f32 v[50:51], v[50:51], v[60:61]
	v_exp_f32_e32 v54, v54
	v_exp_f32_e32 v55, v55
	v_cvt_pk_bf16_f32 v60, v50, v51
	v_cvt_f32_i32_e32 v51, v53
	v_cvt_f32_i32_e32 v50, v52
	v_pk_add_f32 v[52:53], v[54:55], 1.0 op_sel_hi:[1,0]
	v_pk_mul_f32 v[54:55], v[146:147], v[72:73] op_sel_hi:[1,0]
	v_rcp_f32_e32 v52, v52
	v_rcp_f32_e32 v53, v53
	v_pk_mul_f32 v[50:51], v[56:57], v[50:51]
	v_cvt_f32_i32_e32 v47, v47
	v_pk_mul_f32 v[50:51], v[50:51], v[54:55]
	v_cvt_f32_i32_e32 v46, v46
	v_pk_mul_f32 v[50:51], v[50:51], v[52:53]
	v_cvt_f32_i32_e32 v43, v43
	v_cvt_pk_bf16_f32 v61, v50, v51
	v_lshl_add_u64 v[50:51], v[68:69], 0, v[114:115]
	global_store_dwordx4 v[50:51], v[58:61], off sc1 nt
	ds_read_b32 v50, v182 offset:576
	v_cvt_f32_i32_e32 v42, v42
	v_add_u32_e32 v51, s17, v174
	v_cvt_f32_i32_e32 v49, v49
	v_cvt_f32_i32_e32 v48, v48
	s_waitcnt lgkmcnt(0)
	v_pk_mul_f32 v[54:55], v[160:161], v[50:51] op_sel_hi:[1,0]
	v_mul_f32_e32 v56, v50, v50
	v_pk_mul_f32 v[54:55], v[54:55], v[46:47]
	v_pk_mul_f32 v[42:43], v[46:47], v[42:43]
	v_pk_mul_f32 v[46:47], v[158:159], v[56:57] op_sel_hi:[1,0]
	v_cvt_f32_i32_e32 v45, v45
	v_pk_mul_f32 v[42:43], v[42:43], v[46:47]
	v_pk_mul_f32 v[46:47], v[156:157], v[50:51] op_sel_hi:[1,0]
	v_cvt_f32_i32_e32 v44, v44
	v_pk_mul_f32 v[46:47], v[46:47], v[48:49]
	v_exp_f32_e32 v54, v54
	v_exp_f32_e32 v46, v46
	v_exp_f32_e32 v47, v47
	v_exp_f32_e32 v55, v55
	v_cvt_f32_i32_e32 v39, v39
	v_cvt_f32_i32_e32 v38, v38
	v_pk_add_f32 v[46:47], v[46:47], 1.0 op_sel_hi:[1,0]
	v_pk_mul_f32 v[44:45], v[48:49], v[44:45]
	v_rcp_f32_e32 v46, v46
	v_rcp_f32_e32 v47, v47
	v_pk_mul_f32 v[48:49], v[154:155], v[56:57] op_sel_hi:[1,0]
	v_pk_add_f32 v[54:55], v[54:55], 1.0 op_sel_hi:[1,0]
	v_pk_mul_f32 v[44:45], v[44:45], v[48:49]
	v_rcp_f32_e32 v54, v54
	v_pk_mul_f32 v[44:45], v[44:45], v[46:47]
	v_pk_mul_f32 v[46:47], v[152:153], v[50:51] op_sel_hi:[1,0]
	v_rcp_f32_e32 v55, v55
	v_pk_mul_f32 v[46:47], v[46:47], v[38:39]
	v_cvt_f32_i32_e32 v35, v35
	v_exp_f32_e32 v46, v46
	v_exp_f32_e32 v47, v47
	v_cvt_f32_i32_e32 v34, v34
	v_cvt_f32_i32_e32 v41, v41
	v_cvt_f32_i32_e32 v40, v40
	v_pk_mul_f32 v[42:43], v[42:43], v[54:55]
	v_pk_mul_f32 v[34:35], v[38:39], v[34:35]
	v_cvt_pk_bf16_f32 v42, v42, v43
	v_cvt_pk_bf16_f32 v43, v44, v45
	v_pk_add_f32 v[44:45], v[46:47], 1.0 op_sel_hi:[1,0]
	v_pk_mul_f32 v[38:39], v[150:151], v[56:57] op_sel_hi:[1,0]
	v_rcp_f32_e32 v44, v44
	v_rcp_f32_e32 v45, v45
	v_pk_mul_f32 v[34:35], v[34:35], v[38:39]
	v_pk_mul_f32 v[38:39], v[148:149], v[50:51] op_sel_hi:[1,0]
	v_mad_i64_i32 v[52:53], s[28:29], v51, s49, v[162:163]
	v_pk_mul_f32 v[38:39], v[38:39], v[40:41]
	v_pk_mul_f32 v[34:35], v[34:35], v[44:45]
	v_exp_f32_e32 v38, v38
	v_exp_f32_e32 v39, v39
	v_cvt_pk_bf16_f32 v44, v34, v35
	v_cvt_f32_i32_e32 v35, v37
	v_cvt_f32_i32_e32 v34, v36
	v_pk_add_f32 v[36:37], v[38:39], 1.0 op_sel_hi:[1,0]
	v_pk_mul_f32 v[38:39], v[146:147], v[56:57] op_sel_hi:[1,0]
	v_rcp_f32_e32 v36, v36
	v_rcp_f32_e32 v37, v37
	v_pk_mul_f32 v[34:35], v[40:41], v[34:35]
	v_cvt_f32_i32_e32 v31, v31
	v_pk_mul_f32 v[34:35], v[34:35], v[38:39]
	v_cvt_f32_i32_e32 v30, v30
	v_pk_mul_f32 v[34:35], v[34:35], v[36:37]
	v_cvt_f32_i32_e32 v27, v27
	v_cvt_pk_bf16_f32 v45, v34, v35
	v_lshl_add_u64 v[34:35], v[52:53], 0, v[114:115]
	global_store_dwordx4 v[34:35], v[42:45], off sc1 nt
	ds_read_b32 v34, v182 offset:640
	v_cvt_f32_i32_e32 v26, v26
	v_add_u32_e32 v35, s17, v175
	v_cvt_f32_i32_e32 v33, v33
	v_cvt_f32_i32_e32 v32, v32
	s_waitcnt lgkmcnt(0)
	v_pk_mul_f32 v[38:39], v[160:161], v[34:35] op_sel_hi:[1,0]
	v_mul_f32_e32 v40, v34, v34
	v_pk_mul_f32 v[38:39], v[38:39], v[30:31]
	v_pk_mul_f32 v[26:27], v[30:31], v[26:27]
	v_pk_mul_f32 v[30:31], v[158:159], v[40:41] op_sel_hi:[1,0]
	v_cvt_f32_i32_e32 v29, v29
	v_pk_mul_f32 v[26:27], v[26:27], v[30:31]
	v_pk_mul_f32 v[30:31], v[156:157], v[34:35] op_sel_hi:[1,0]
	v_cvt_f32_i32_e32 v28, v28
	v_pk_mul_f32 v[30:31], v[30:31], v[32:33]
	v_exp_f32_e32 v38, v38
	v_exp_f32_e32 v30, v30
	v_exp_f32_e32 v31, v31
	v_exp_f32_e32 v39, v39
	v_cvt_f32_i32_e32 v23, v23
	v_cvt_f32_i32_e32 v22, v22
	v_pk_add_f32 v[30:31], v[30:31], 1.0 op_sel_hi:[1,0]
	v_pk_mul_f32 v[28:29], v[32:33], v[28:29]
	v_rcp_f32_e32 v30, v30
	v_rcp_f32_e32 v31, v31
	v_pk_mul_f32 v[32:33], v[154:155], v[40:41] op_sel_hi:[1,0]
	v_pk_add_f32 v[38:39], v[38:39], 1.0 op_sel_hi:[1,0]
	v_pk_mul_f32 v[28:29], v[28:29], v[32:33]
	v_rcp_f32_e32 v38, v38
	v_pk_mul_f32 v[28:29], v[28:29], v[30:31]
	v_pk_mul_f32 v[30:31], v[152:153], v[34:35] op_sel_hi:[1,0]
	v_rcp_f32_e32 v39, v39
	v_pk_mul_f32 v[30:31], v[30:31], v[22:23]
	v_cvt_f32_i32_e32 v19, v19
	v_exp_f32_e32 v30, v30
	v_exp_f32_e32 v31, v31
	v_cvt_f32_i32_e32 v18, v18
	v_cvt_f32_i32_e32 v25, v25
	v_cvt_f32_i32_e32 v24, v24
	v_pk_mul_f32 v[26:27], v[26:27], v[38:39]
	v_pk_mul_f32 v[18:19], v[22:23], v[18:19]
	v_cvt_pk_bf16_f32 v26, v26, v27
	v_cvt_pk_bf16_f32 v27, v28, v29
	v_pk_add_f32 v[28:29], v[30:31], 1.0 op_sel_hi:[1,0]
	v_pk_mul_f32 v[22:23], v[150:151], v[40:41] op_sel_hi:[1,0]
	v_rcp_f32_e32 v28, v28
	v_rcp_f32_e32 v29, v29
	v_pk_mul_f32 v[18:19], v[18:19], v[22:23]
	v_pk_mul_f32 v[22:23], v[148:149], v[34:35] op_sel_hi:[1,0]
	v_mad_i64_i32 v[36:37], s[28:29], v35, s49, v[162:163]
	v_pk_mul_f32 v[22:23], v[22:23], v[24:25]
	v_pk_mul_f32 v[18:19], v[18:19], v[28:29]
	v_exp_f32_e32 v22, v22
	v_exp_f32_e32 v23, v23
	v_cvt_pk_bf16_f32 v28, v18, v19
	v_cvt_f32_i32_e32 v19, v21
	v_cvt_f32_i32_e32 v18, v20
	v_pk_add_f32 v[20:21], v[22:23], 1.0 op_sel_hi:[1,0]
	v_pk_mul_f32 v[22:23], v[146:147], v[40:41] op_sel_hi:[1,0]
	v_rcp_f32_e32 v20, v20
	v_rcp_f32_e32 v21, v21
	v_pk_mul_f32 v[18:19], v[24:25], v[18:19]
	v_cvt_f32_i32_e32 v15, v15
	v_pk_mul_f32 v[18:19], v[18:19], v[22:23]
	v_cvt_f32_i32_e32 v14, v14
	v_pk_mul_f32 v[18:19], v[18:19], v[20:21]
	v_cvt_f32_i32_e32 v11, v11
	v_cvt_pk_bf16_f32 v29, v18, v19
	v_lshl_add_u64 v[18:19], v[36:37], 0, v[114:115]
	global_store_dwordx4 v[18:19], v[26:29], off sc1 nt
	ds_read_b32 v18, v182 offset:704
	v_cvt_f32_i32_e32 v10, v10
	v_add_u32_e32 v19, s17, v176
	v_cvt_f32_i32_e32 v17, v17
	v_cvt_f32_i32_e32 v16, v16
	s_waitcnt lgkmcnt(0)
	v_pk_mul_f32 v[22:23], v[160:161], v[18:19] op_sel_hi:[1,0]
	v_mul_f32_e32 v24, v18, v18
	v_pk_mul_f32 v[22:23], v[22:23], v[14:15]
	v_pk_mul_f32 v[10:11], v[14:15], v[10:11]
	v_pk_mul_f32 v[14:15], v[158:159], v[24:25] op_sel_hi:[1,0]
	v_cvt_f32_i32_e32 v13, v13
	v_pk_mul_f32 v[10:11], v[10:11], v[14:15]
	v_pk_mul_f32 v[14:15], v[156:157], v[18:19] op_sel_hi:[1,0]
	v_cvt_f32_i32_e32 v12, v12
	v_pk_mul_f32 v[14:15], v[14:15], v[16:17]
	v_exp_f32_e32 v22, v22
	v_exp_f32_e32 v14, v14
	v_exp_f32_e32 v15, v15
	v_exp_f32_e32 v23, v23
	v_cvt_f32_i32_e32 v7, v7
	v_cvt_f32_i32_e32 v6, v6
	v_pk_add_f32 v[14:15], v[14:15], 1.0 op_sel_hi:[1,0]
	v_pk_mul_f32 v[12:13], v[16:17], v[12:13]
	v_rcp_f32_e32 v14, v14
	v_rcp_f32_e32 v15, v15
	v_pk_mul_f32 v[16:17], v[154:155], v[24:25] op_sel_hi:[1,0]
	v_pk_add_f32 v[22:23], v[22:23], 1.0 op_sel_hi:[1,0]
	v_pk_mul_f32 v[12:13], v[12:13], v[16:17]
	v_rcp_f32_e32 v22, v22
	v_pk_mul_f32 v[12:13], v[12:13], v[14:15]
	v_pk_mul_f32 v[14:15], v[152:153], v[18:19] op_sel_hi:[1,0]
	v_rcp_f32_e32 v23, v23
	v_pk_mul_f32 v[14:15], v[14:15], v[6:7]
	v_cvt_f32_i32_e32 v3, v3
	v_exp_f32_e32 v14, v14
	v_exp_f32_e32 v15, v15
	v_cvt_f32_i32_e32 v2, v2
	v_cvt_f32_i32_e32 v9, v9
	v_cvt_f32_i32_e32 v8, v8
	v_pk_mul_f32 v[10:11], v[10:11], v[22:23]
	v_pk_mul_f32 v[2:3], v[6:7], v[2:3]
	v_cvt_pk_bf16_f32 v10, v10, v11
	v_cvt_pk_bf16_f32 v11, v12, v13
	v_pk_add_f32 v[12:13], v[14:15], 1.0 op_sel_hi:[1,0]
	v_pk_mul_f32 v[6:7], v[150:151], v[24:25] op_sel_hi:[1,0]
	v_rcp_f32_e32 v12, v12
	v_rcp_f32_e32 v13, v13
	v_pk_mul_f32 v[2:3], v[2:3], v[6:7]
	v_pk_mul_f32 v[6:7], v[148:149], v[18:19] op_sel_hi:[1,0]
	v_mad_i64_i32 v[20:21], s[28:29], v19, s49, v[162:163]
	v_pk_mul_f32 v[6:7], v[6:7], v[8:9]
	v_pk_mul_f32 v[2:3], v[2:3], v[12:13]
	v_exp_f32_e32 v6, v6
	v_exp_f32_e32 v7, v7
	v_cvt_pk_bf16_f32 v12, v2, v3
	v_cvt_f32_i32_e32 v3, v5
	v_cvt_f32_i32_e32 v2, v4
	v_pk_add_f32 v[4:5], v[6:7], 1.0 op_sel_hi:[1,0]
	v_pk_mul_f32 v[6:7], v[146:147], v[24:25] op_sel_hi:[1,0]
	v_rcp_f32_e32 v4, v4
	v_rcp_f32_e32 v5, v5
	v_pk_mul_f32 v[2:3], v[8:9], v[2:3]
	s_andn2_b64 vcc, exec, s[0:1]
	v_pk_mul_f32 v[2:3], v[2:3], v[6:7]
	s_mov_b64 s[0:1], -1
	v_pk_mul_f32 v[2:3], v[2:3], v[4:5]
	s_nop 0
	v_cvt_pk_bf16_f32 v13, v2, v3
	v_lshl_add_u64 v[2:3], v[20:21], 0, v[114:115]
	global_store_dwordx4 v[2:3], v[10:13], off sc1 nt
	s_cbranch_vccnz .LBB0_2466
	s_andn2_b64 vcc, exec, s[10:11]
	s_cbranch_vccnz .LBB0_2465
	s_barrier
	s_branch .LBB0_2465

.LBB0_3390:
	s_lshl_b32 s17, s49, 11
	s_add_i32 s17, s17, 0
	s_add_i32 s19, s17, 0x20180
	s_lshl_b32 s17, s42, 2
	s_add_i32 s17, s19, s17
	v_lshl_add_u32 v154, v164, 2, s17
	ds_read_b128 v[146:149], v154 offset:1024
	ds_read_b128 v[150:153], v154 offset:1536
	ds_read_b128 v[182:185], v154 offset:1040
	ds_read_b128 v[186:189], v154 offset:1552
	v_lshl_add_u32 v181, v165, 2, s19
	s_waitcnt lgkmcnt(0)
	v_pk_mul_f32 v[160:161], v[146:147], s[14:15] op_sel_hi:[1,0]
	v_pk_mul_f32 v[156:157], v[148:149], s[14:15] op_sel_hi:[1,0]
	v_pk_mul_f32 v[154:155], v[148:149], v[152:153]
	v_pk_mul_f32 v[158:159], v[146:147], v[150:151]
	v_pk_mul_f32 v[148:149], v[184:185], s[14:15] op_sel_hi:[1,0]
	v_pk_mul_f32 v[146:147], v[184:185], v[188:189]
	ds_read_b32 v184, v181
	v_cvt_f32_i32_e32 v127, v127
	v_cvt_f32_i32_e32 v126, v126
	v_cvt_f32_i32_e32 v123, v123
	v_cvt_f32_i32_e32 v122, v122
	s_lshl_b32 s17, s24, 8
	v_add_u32_e32 v185, s17, v165
	v_cvt_f32_i32_e32 v129, v129
	v_cvt_f32_i32_e32 v128, v128
	s_waitcnt lgkmcnt(0)
	v_pk_mul_f32 v[188:189], v[160:161], v[184:185] op_sel_hi:[1,0]
	v_mul_f32_e32 v190, v184, v184
	v_pk_mul_f32 v[188:189], v[188:189], v[126:127]
	v_pk_mul_f32 v[122:123], v[126:127], v[122:123]
	v_pk_mul_f32 v[126:127], v[158:159], v[190:191] op_sel_hi:[1,0]
	v_cvt_f32_i32_e32 v125, v125
	v_pk_mul_f32 v[122:123], v[122:123], v[126:127]
	v_pk_mul_f32 v[126:127], v[156:157], v[184:185] op_sel_hi:[1,0]
	v_cvt_f32_i32_e32 v124, v124
	v_pk_mul_f32 v[126:127], v[126:127], v[128:129]
	v_exp_f32_e32 v188, v188
	v_exp_f32_e32 v126, v126
	v_exp_f32_e32 v127, v127
	v_exp_f32_e32 v189, v189
	v_cvt_f32_i32_e32 v119, v119
	v_cvt_f32_i32_e32 v118, v118
	v_pk_add_f32 v[126:127], v[126:127], 1.0 op_sel_hi:[1,0]
	v_pk_mul_f32 v[124:125], v[128:129], v[124:125]
	v_rcp_f32_e32 v126, v126
	v_rcp_f32_e32 v127, v127
	v_pk_mul_f32 v[128:129], v[154:155], v[190:191] op_sel_hi:[1,0]
	v_pk_mul_f32 v[152:153], v[182:183], s[14:15] op_sel_hi:[1,0]
	v_pk_mul_f32 v[124:125], v[124:125], v[128:129]
	v_pk_add_f32 v[188:189], v[188:189], 1.0 op_sel_hi:[1,0]
	v_pk_mul_f32 v[124:125], v[124:125], v[126:127]
	v_pk_mul_f32 v[126:127], v[152:153], v[184:185] op_sel_hi:[1,0]
	v_rcp_f32_e32 v188, v188
	v_rcp_f32_e32 v189, v189
	v_pk_mul_f32 v[126:127], v[126:127], v[118:119]
	v_cvt_f32_i32_e32 v115, v115
	v_exp_f32_e32 v126, v126
	v_exp_f32_e32 v127, v127
	v_cvt_f32_i32_e32 v114, v114
	v_cvt_f32_i32_e32 v121, v121
	v_cvt_f32_i32_e32 v120, v120
	v_pk_mul_f32 v[150:151], v[182:183], v[186:187]
	v_pk_mul_f32 v[122:123], v[122:123], v[188:189]
	v_pk_mul_f32 v[114:115], v[118:119], v[114:115]
	v_cvt_pk_bf16_f32 v122, v122, v123
	v_cvt_pk_bf16_f32 v123, v124, v125
	v_pk_add_f32 v[124:125], v[126:127], 1.0 op_sel_hi:[1,0]
	v_pk_mul_f32 v[118:119], v[150:151], v[190:191] op_sel_hi:[1,0]
	v_rcp_f32_e32 v124, v124
	v_rcp_f32_e32 v125, v125
	v_pk_mul_f32 v[114:115], v[114:115], v[118:119]
	v_pk_mul_f32 v[118:119], v[148:149], v[184:185] op_sel_hi:[1,0]
	v_lshl_or_b32 v182, s48, 7, v176
	v_pk_mul_f32 v[118:119], v[118:119], v[120:121]
	v_pk_mul_f32 v[114:115], v[114:115], v[124:125]
	v_exp_f32_e32 v118, v118
	v_exp_f32_e32 v119, v119
	v_cvt_pk_bf16_f32 v124, v114, v115
	v_cvt_f32_i32_e32 v115, v117
	v_cvt_f32_i32_e32 v114, v116
	v_pk_add_f32 v[116:117], v[118:119], 1.0 op_sel_hi:[1,0]
	v_pk_mul_f32 v[118:119], v[146:147], v[190:191] op_sel_hi:[1,0]
	v_rcp_f32_e32 v116, v116
	v_rcp_f32_e32 v117, v117
	v_pk_mul_f32 v[114:115], v[120:121], v[114:115]
	v_ashrrev_i32_e32 v183, 31, v182
	v_pk_mul_f32 v[114:115], v[114:115], v[118:119]
	v_mov_b64_e32 v[162:163], s[60:61]
	v_pk_mul_f32 v[114:115], v[114:115], v[116:117]
	v_mad_i64_i32 v[186:187], s[26:27], v185, s46, v[162:163]
	v_cvt_pk_bf16_f32 v125, v114, v115
	v_lshlrev_b64 v[114:115], 1, v[182:183]
	v_lshl_add_u64 v[116:117], v[186:187], 0, v[114:115]
	global_store_dwordx4 v[116:117], v[122:125], off sc1 nt
	ds_read_b32 v116, v181 offset:64
	v_cvt_f32_i32_e32 v111, v111
	v_cvt_f32_i32_e32 v110, v110
	v_cvt_f32_i32_e32 v107, v107
	v_cvt_f32_i32_e32 v106, v106
	v_add_u32_e32 v117, s17, v169
	v_cvt_f32_i32_e32 v113, v113
	v_cvt_f32_i32_e32 v112, v112
	s_waitcnt lgkmcnt(0)
	v_pk_mul_f32 v[120:121], v[160:161], v[116:117] op_sel_hi:[1,0]
	v_mul_f32_e32 v122, v116, v116
	v_pk_mul_f32 v[120:121], v[120:121], v[110:111]
	v_pk_mul_f32 v[106:107], v[110:111], v[106:107]
	v_pk_mul_f32 v[110:111], v[158:159], v[122:123] op_sel_hi:[1,0]
	v_cvt_f32_i32_e32 v109, v109
	v_pk_mul_f32 v[106:107], v[106:107], v[110:111]
	v_pk_mul_f32 v[110:111], v[156:157], v[116:117] op_sel_hi:[1,0]
	v_cvt_f32_i32_e32 v108, v108
	v_pk_mul_f32 v[110:111], v[110:111], v[112:113]
	v_exp_f32_e32 v120, v120
	v_exp_f32_e32 v110, v110
	v_exp_f32_e32 v111, v111
	v_exp_f32_e32 v121, v121
	v_cvt_f32_i32_e32 v103, v103
	v_cvt_f32_i32_e32 v102, v102
	v_pk_add_f32 v[110:111], v[110:111], 1.0 op_sel_hi:[1,0]
	v_pk_mul_f32 v[108:109], v[112:113], v[108:109]
	v_rcp_f32_e32 v110, v110
	v_rcp_f32_e32 v111, v111
	v_pk_mul_f32 v[112:113], v[154:155], v[122:123] op_sel_hi:[1,0]
	v_pk_add_f32 v[120:121], v[120:121], 1.0 op_sel_hi:[1,0]
	v_pk_mul_f32 v[108:109], v[108:109], v[112:113]
	v_rcp_f32_e32 v120, v120
	v_pk_mul_f32 v[108:109], v[108:109], v[110:111]
	v_pk_mul_f32 v[110:111], v[152:153], v[116:117] op_sel_hi:[1,0]
	v_rcp_f32_e32 v121, v121
	v_pk_mul_f32 v[110:111], v[110:111], v[102:103]
	v_cvt_f32_i32_e32 v99, v99
	v_exp_f32_e32 v110, v110
	v_exp_f32_e32 v111, v111
	v_cvt_f32_i32_e32 v98, v98
	v_cvt_f32_i32_e32 v105, v105
	v_cvt_f32_i32_e32 v104, v104
	v_pk_mul_f32 v[106:107], v[106:107], v[120:121]
	v_pk_mul_f32 v[98:99], v[102:103], v[98:99]
	v_cvt_pk_bf16_f32 v106, v106, v107
	v_cvt_pk_bf16_f32 v107, v108, v109
	v_pk_add_f32 v[108:109], v[110:111], 1.0 op_sel_hi:[1,0]
	v_pk_mul_f32 v[102:103], v[150:151], v[122:123] op_sel_hi:[1,0]
	v_rcp_f32_e32 v108, v108
	v_rcp_f32_e32 v109, v109
	v_pk_mul_f32 v[98:99], v[98:99], v[102:103]
	v_pk_mul_f32 v[102:103], v[148:149], v[116:117] op_sel_hi:[1,0]
	v_mad_i64_i32 v[118:119], s[26:27], v117, s46, v[162:163]
	v_pk_mul_f32 v[102:103], v[102:103], v[104:105]
	v_pk_mul_f32 v[98:99], v[98:99], v[108:109]
	v_exp_f32_e32 v102, v102
	v_exp_f32_e32 v103, v103
	v_cvt_pk_bf16_f32 v108, v98, v99
	v_cvt_f32_i32_e32 v99, v101
	v_cvt_f32_i32_e32 v98, v100
	v_pk_add_f32 v[100:101], v[102:103], 1.0 op_sel_hi:[1,0]
	v_pk_mul_f32 v[102:103], v[146:147], v[122:123] op_sel_hi:[1,0]
	v_rcp_f32_e32 v100, v100
	v_rcp_f32_e32 v101, v101
	v_pk_mul_f32 v[98:99], v[104:105], v[98:99]
	v_cvt_f32_i32_e32 v95, v95
	v_pk_mul_f32 v[98:99], v[98:99], v[102:103]
	v_cvt_f32_i32_e32 v94, v94
	v_pk_mul_f32 v[98:99], v[98:99], v[100:101]
	v_cvt_f32_i32_e32 v91, v91
	v_cvt_pk_bf16_f32 v109, v98, v99
	v_lshl_add_u64 v[98:99], v[118:119], 0, v[114:115]
	global_store_dwordx4 v[98:99], v[106:109], off sc1 nt
	ds_read_b32 v98, v181 offset:128
	v_cvt_f32_i32_e32 v90, v90
	v_add_u32_e32 v99, s17, v170
	v_cvt_f32_i32_e32 v97, v97
	v_cvt_f32_i32_e32 v96, v96
	s_waitcnt lgkmcnt(0)
	v_pk_mul_f32 v[102:103], v[160:161], v[98:99] op_sel_hi:[1,0]
	v_mul_f32_e32 v104, v98, v98
	v_pk_mul_f32 v[102:103], v[102:103], v[94:95]
	v_pk_mul_f32 v[90:91], v[94:95], v[90:91]
	v_pk_mul_f32 v[94:95], v[158:159], v[104:105] op_sel_hi:[1,0]
	v_cvt_f32_i32_e32 v93, v93
	v_pk_mul_f32 v[90:91], v[90:91], v[94:95]
	v_pk_mul_f32 v[94:95], v[156:157], v[98:99] op_sel_hi:[1,0]
	v_cvt_f32_i32_e32 v92, v92
	v_pk_mul_f32 v[94:95], v[94:95], v[96:97]
	v_exp_f32_e32 v102, v102
	v_exp_f32_e32 v94, v94
	v_exp_f32_e32 v95, v95
	v_exp_f32_e32 v103, v103
	v_cvt_f32_i32_e32 v87, v87
	v_cvt_f32_i32_e32 v86, v86
	v_pk_add_f32 v[94:95], v[94:95], 1.0 op_sel_hi:[1,0]
	v_pk_mul_f32 v[92:93], v[96:97], v[92:93]
	v_rcp_f32_e32 v94, v94
	v_rcp_f32_e32 v95, v95
	v_pk_mul_f32 v[96:97], v[154:155], v[104:105] op_sel_hi:[1,0]
	v_pk_add_f32 v[102:103], v[102:103], 1.0 op_sel_hi:[1,0]
	v_pk_mul_f32 v[92:93], v[92:93], v[96:97]
	v_rcp_f32_e32 v102, v102
	v_pk_mul_f32 v[92:93], v[92:93], v[94:95]
	v_pk_mul_f32 v[94:95], v[152:153], v[98:99] op_sel_hi:[1,0]
	v_rcp_f32_e32 v103, v103
	v_pk_mul_f32 v[94:95], v[94:95], v[86:87]
	v_cvt_f32_i32_e32 v83, v83
	v_exp_f32_e32 v94, v94
	v_exp_f32_e32 v95, v95
	v_cvt_f32_i32_e32 v82, v82
	v_cvt_f32_i32_e32 v89, v89
	v_cvt_f32_i32_e32 v88, v88
	v_pk_mul_f32 v[90:91], v[90:91], v[102:103]
	v_pk_mul_f32 v[82:83], v[86:87], v[82:83]
	v_cvt_pk_bf16_f32 v90, v90, v91
	v_cvt_pk_bf16_f32 v91, v92, v93
	v_pk_add_f32 v[92:93], v[94:95], 1.0 op_sel_hi:[1,0]
	v_pk_mul_f32 v[86:87], v[150:151], v[104:105] op_sel_hi:[1,0]
	v_rcp_f32_e32 v92, v92
	v_rcp_f32_e32 v93, v93
	v_pk_mul_f32 v[82:83], v[82:83], v[86:87]
	v_pk_mul_f32 v[86:87], v[148:149], v[98:99] op_sel_hi:[1,0]
	v_mad_i64_i32 v[100:101], s[26:27], v99, s46, v[162:163]
	v_pk_mul_f32 v[86:87], v[86:87], v[88:89]
	v_pk_mul_f32 v[82:83], v[82:83], v[92:93]
	v_exp_f32_e32 v86, v86
	v_exp_f32_e32 v87, v87
	v_cvt_pk_bf16_f32 v92, v82, v83
	v_cvt_f32_i32_e32 v83, v85
	v_cvt_f32_i32_e32 v82, v84
	v_pk_add_f32 v[84:85], v[86:87], 1.0 op_sel_hi:[1,0]
	v_pk_mul_f32 v[86:87], v[146:147], v[104:105] op_sel_hi:[1,0]
	v_rcp_f32_e32 v84, v84
	v_rcp_f32_e32 v85, v85
	v_pk_mul_f32 v[82:83], v[88:89], v[82:83]
	v_cvt_f32_i32_e32 v79, v79
	v_pk_mul_f32 v[82:83], v[82:83], v[86:87]
	v_cvt_f32_i32_e32 v78, v78
	v_pk_mul_f32 v[82:83], v[82:83], v[84:85]
	v_cvt_f32_i32_e32 v75, v75
	v_cvt_pk_bf16_f32 v93, v82, v83
	v_lshl_add_u64 v[82:83], v[100:101], 0, v[114:115]
	global_store_dwordx4 v[82:83], v[90:93], off sc1 nt
	ds_read_b32 v82, v181 offset:192
	v_cvt_f32_i32_e32 v74, v74
	v_add_u32_e32 v83, s17, v171
	v_cvt_f32_i32_e32 v81, v81
	v_cvt_f32_i32_e32 v80, v80
	s_waitcnt lgkmcnt(0)
	v_pk_mul_f32 v[86:87], v[160:161], v[82:83] op_sel_hi:[1,0]
	v_mul_f32_e32 v88, v82, v82
	v_pk_mul_f32 v[86:87], v[86:87], v[78:79]
	v_pk_mul_f32 v[74:75], v[78:79], v[74:75]
	v_pk_mul_f32 v[78:79], v[158:159], v[88:89] op_sel_hi:[1,0]
	v_cvt_f32_i32_e32 v77, v77
	v_pk_mul_f32 v[74:75], v[74:75], v[78:79]
	v_pk_mul_f32 v[78:79], v[156:157], v[82:83] op_sel_hi:[1,0]
	v_cvt_f32_i32_e32 v76, v76
	v_pk_mul_f32 v[78:79], v[78:79], v[80:81]
	v_exp_f32_e32 v86, v86
	v_exp_f32_e32 v78, v78
	v_exp_f32_e32 v79, v79
	v_exp_f32_e32 v87, v87
	v_cvt_f32_i32_e32 v71, v71
	v_cvt_f32_i32_e32 v70, v70
	v_pk_add_f32 v[78:79], v[78:79], 1.0 op_sel_hi:[1,0]
	v_pk_mul_f32 v[76:77], v[80:81], v[76:77]
	v_rcp_f32_e32 v78, v78
	v_rcp_f32_e32 v79, v79
	v_pk_mul_f32 v[80:81], v[154:155], v[88:89] op_sel_hi:[1,0]
	v_pk_add_f32 v[86:87], v[86:87], 1.0 op_sel_hi:[1,0]
	v_pk_mul_f32 v[76:77], v[76:77], v[80:81]
	v_rcp_f32_e32 v86, v86
	v_pk_mul_f32 v[76:77], v[76:77], v[78:79]
	v_pk_mul_f32 v[78:79], v[152:153], v[82:83] op_sel_hi:[1,0]
	v_rcp_f32_e32 v87, v87
	v_pk_mul_f32 v[78:79], v[78:79], v[70:71]
	v_cvt_f32_i32_e32 v67, v67
	v_exp_f32_e32 v78, v78
	v_exp_f32_e32 v79, v79
	v_cvt_f32_i32_e32 v66, v66
	v_cvt_f32_i32_e32 v73, v73
	v_cvt_f32_i32_e32 v72, v72
	v_pk_mul_f32 v[74:75], v[74:75], v[86:87]
	v_pk_mul_f32 v[66:67], v[70:71], v[66:67]
	v_cvt_pk_bf16_f32 v74, v74, v75
	v_cvt_pk_bf16_f32 v75, v76, v77
	v_pk_add_f32 v[76:77], v[78:79], 1.0 op_sel_hi:[1,0]
	v_pk_mul_f32 v[70:71], v[150:151], v[88:89] op_sel_hi:[1,0]
	v_rcp_f32_e32 v76, v76
	v_rcp_f32_e32 v77, v77
	v_pk_mul_f32 v[66:67], v[66:67], v[70:71]
	v_pk_mul_f32 v[70:71], v[148:149], v[82:83] op_sel_hi:[1,0]
	v_mad_i64_i32 v[84:85], s[26:27], v83, s46, v[162:163]
	v_pk_mul_f32 v[70:71], v[70:71], v[72:73]
	v_pk_mul_f32 v[66:67], v[66:67], v[76:77]
	v_exp_f32_e32 v70, v70
	v_exp_f32_e32 v71, v71
	v_cvt_pk_bf16_f32 v76, v66, v67
	v_cvt_f32_i32_e32 v67, v69
	v_cvt_f32_i32_e32 v66, v68
	v_pk_add_f32 v[68:69], v[70:71], 1.0 op_sel_hi:[1,0]
	v_pk_mul_f32 v[70:71], v[146:147], v[88:89] op_sel_hi:[1,0]
	v_rcp_f32_e32 v68, v68
	v_rcp_f32_e32 v69, v69
	v_pk_mul_f32 v[66:67], v[72:73], v[66:67]
	v_cvt_f32_i32_e32 v63, v63
	v_pk_mul_f32 v[66:67], v[66:67], v[70:71]
	v_cvt_f32_i32_e32 v62, v62
	v_pk_mul_f32 v[66:67], v[66:67], v[68:69]
	v_cvt_f32_i32_e32 v59, v59
	v_cvt_pk_bf16_f32 v77, v66, v67
	v_lshl_add_u64 v[66:67], v[84:85], 0, v[114:115]
	global_store_dwordx4 v[66:67], v[74:77], off sc1 nt
	ds_read_b32 v66, v181 offset:512
	v_cvt_f32_i32_e32 v58, v58
	v_add_u32_e32 v67, s17, v172
	v_cvt_f32_i32_e32 v65, v65
	v_cvt_f32_i32_e32 v64, v64
	s_waitcnt lgkmcnt(0)
	v_pk_mul_f32 v[70:71], v[160:161], v[66:67] op_sel_hi:[1,0]
	v_mul_f32_e32 v72, v66, v66
	v_pk_mul_f32 v[70:71], v[70:71], v[62:63]
	v_pk_mul_f32 v[58:59], v[62:63], v[58:59]
	v_pk_mul_f32 v[62:63], v[158:159], v[72:73] op_sel_hi:[1,0]
	v_cvt_f32_i32_e32 v61, v61
	v_pk_mul_f32 v[58:59], v[58:59], v[62:63]
	v_pk_mul_f32 v[62:63], v[156:157], v[66:67] op_sel_hi:[1,0]
	v_cvt_f32_i32_e32 v60, v60
	v_pk_mul_f32 v[62:63], v[62:63], v[64:65]
	v_exp_f32_e32 v70, v70
	v_exp_f32_e32 v62, v62
	v_exp_f32_e32 v63, v63
	v_exp_f32_e32 v71, v71
	v_cvt_f32_i32_e32 v55, v55
	v_cvt_f32_i32_e32 v54, v54
	v_pk_add_f32 v[62:63], v[62:63], 1.0 op_sel_hi:[1,0]
	v_pk_mul_f32 v[60:61], v[64:65], v[60:61]
	v_rcp_f32_e32 v62, v62
	v_rcp_f32_e32 v63, v63
	v_pk_mul_f32 v[64:65], v[154:155], v[72:73] op_sel_hi:[1,0]
	v_pk_add_f32 v[70:71], v[70:71], 1.0 op_sel_hi:[1,0]
	v_pk_mul_f32 v[60:61], v[60:61], v[64:65]
	v_rcp_f32_e32 v70, v70
	v_pk_mul_f32 v[60:61], v[60:61], v[62:63]
	v_pk_mul_f32 v[62:63], v[152:153], v[66:67] op_sel_hi:[1,0]
	v_rcp_f32_e32 v71, v71
	v_pk_mul_f32 v[62:63], v[62:63], v[54:55]
	v_cvt_f32_i32_e32 v51, v51
	v_exp_f32_e32 v62, v62
	v_exp_f32_e32 v63, v63
	v_cvt_f32_i32_e32 v50, v50
	v_cvt_f32_i32_e32 v57, v57
	v_cvt_f32_i32_e32 v56, v56
	v_pk_mul_f32 v[58:59], v[58:59], v[70:71]
	v_pk_mul_f32 v[50:51], v[54:55], v[50:51]
	v_cvt_pk_bf16_f32 v58, v58, v59
	v_cvt_pk_bf16_f32 v59, v60, v61
	v_pk_add_f32 v[60:61], v[62:63], 1.0 op_sel_hi:[1,0]
	v_pk_mul_f32 v[54:55], v[150:151], v[72:73] op_sel_hi:[1,0]
	v_rcp_f32_e32 v60, v60
	v_rcp_f32_e32 v61, v61
	v_pk_mul_f32 v[50:51], v[50:51], v[54:55]
	v_pk_mul_f32 v[54:55], v[148:149], v[66:67] op_sel_hi:[1,0]
	v_mad_i64_i32 v[68:69], s[26:27], v67, s46, v[162:163]
	v_pk_mul_f32 v[54:55], v[54:55], v[56:57]
	v_pk_mul_f32 v[50:51], v[50:51], v[60:61]
	v_exp_f32_e32 v54, v54
	v_exp_f32_e32 v55, v55
	v_cvt_pk_bf16_f32 v60, v50, v51
	v_cvt_f32_i32_e32 v51, v53
	v_cvt_f32_i32_e32 v50, v52
	v_pk_add_f32 v[52:53], v[54:55], 1.0 op_sel_hi:[1,0]
	v_pk_mul_f32 v[54:55], v[146:147], v[72:73] op_sel_hi:[1,0]
	v_rcp_f32_e32 v52, v52
	v_rcp_f32_e32 v53, v53
	v_pk_mul_f32 v[50:51], v[56:57], v[50:51]
	v_cvt_f32_i32_e32 v47, v47
	v_pk_mul_f32 v[50:51], v[50:51], v[54:55]
	v_cvt_f32_i32_e32 v46, v46
	v_pk_mul_f32 v[50:51], v[50:51], v[52:53]
	v_cvt_f32_i32_e32 v43, v43
	v_cvt_pk_bf16_f32 v61, v50, v51
	v_lshl_add_u64 v[50:51], v[68:69], 0, v[114:115]
	global_store_dwordx4 v[50:51], v[58:61], off sc1 nt
	ds_read_b32 v50, v181 offset:576
	v_cvt_f32_i32_e32 v42, v42
	v_add_u32_e32 v51, s17, v173
	v_cvt_f32_i32_e32 v49, v49
	v_cvt_f32_i32_e32 v48, v48
	s_waitcnt lgkmcnt(0)
	v_pk_mul_f32 v[54:55], v[160:161], v[50:51] op_sel_hi:[1,0]
	v_mul_f32_e32 v56, v50, v50
	v_pk_mul_f32 v[54:55], v[54:55], v[46:47]
	v_pk_mul_f32 v[42:43], v[46:47], v[42:43]
	v_pk_mul_f32 v[46:47], v[158:159], v[56:57] op_sel_hi:[1,0]
	v_cvt_f32_i32_e32 v45, v45
	v_pk_mul_f32 v[42:43], v[42:43], v[46:47]
	v_pk_mul_f32 v[46:47], v[156:157], v[50:51] op_sel_hi:[1,0]
	v_cvt_f32_i32_e32 v44, v44
	v_pk_mul_f32 v[46:47], v[46:47], v[48:49]
	v_exp_f32_e32 v54, v54
	v_exp_f32_e32 v46, v46
	v_exp_f32_e32 v47, v47
	v_exp_f32_e32 v55, v55
	v_cvt_f32_i32_e32 v39, v39
	v_cvt_f32_i32_e32 v38, v38
	v_pk_add_f32 v[46:47], v[46:47], 1.0 op_sel_hi:[1,0]
	v_pk_mul_f32 v[44:45], v[48:49], v[44:45]
	v_rcp_f32_e32 v46, v46
	v_rcp_f32_e32 v47, v47
	v_pk_mul_f32 v[48:49], v[154:155], v[56:57] op_sel_hi:[1,0]
	v_pk_add_f32 v[54:55], v[54:55], 1.0 op_sel_hi:[1,0]
	v_pk_mul_f32 v[44:45], v[44:45], v[48:49]
	v_rcp_f32_e32 v54, v54
	v_pk_mul_f32 v[44:45], v[44:45], v[46:47]
	v_pk_mul_f32 v[46:47], v[152:153], v[50:51] op_sel_hi:[1,0]
	v_rcp_f32_e32 v55, v55
	v_pk_mul_f32 v[46:47], v[46:47], v[38:39]
	v_cvt_f32_i32_e32 v35, v35
	v_exp_f32_e32 v46, v46
	v_exp_f32_e32 v47, v47
	v_cvt_f32_i32_e32 v34, v34
	v_cvt_f32_i32_e32 v41, v41
	v_cvt_f32_i32_e32 v40, v40
	v_pk_mul_f32 v[42:43], v[42:43], v[54:55]
	v_pk_mul_f32 v[34:35], v[38:39], v[34:35]
	v_cvt_pk_bf16_f32 v42, v42, v43
	v_cvt_pk_bf16_f32 v43, v44, v45
	v_pk_add_f32 v[44:45], v[46:47], 1.0 op_sel_hi:[1,0]
	v_pk_mul_f32 v[38:39], v[150:151], v[56:57] op_sel_hi:[1,0]
	v_rcp_f32_e32 v44, v44
	v_rcp_f32_e32 v45, v45
	v_pk_mul_f32 v[34:35], v[34:35], v[38:39]
	v_pk_mul_f32 v[38:39], v[148:149], v[50:51] op_sel_hi:[1,0]
	v_mad_i64_i32 v[52:53], s[26:27], v51, s46, v[162:163]
	v_pk_mul_f32 v[38:39], v[38:39], v[40:41]
	v_pk_mul_f32 v[34:35], v[34:35], v[44:45]
	v_exp_f32_e32 v38, v38
	v_exp_f32_e32 v39, v39
	v_cvt_pk_bf16_f32 v44, v34, v35
	v_cvt_f32_i32_e32 v35, v37
	v_cvt_f32_i32_e32 v34, v36
	v_pk_add_f32 v[36:37], v[38:39], 1.0 op_sel_hi:[1,0]
	v_pk_mul_f32 v[38:39], v[146:147], v[56:57] op_sel_hi:[1,0]
	v_rcp_f32_e32 v36, v36
	v_rcp_f32_e32 v37, v37
	v_pk_mul_f32 v[34:35], v[40:41], v[34:35]
	v_cvt_f32_i32_e32 v31, v31
	v_pk_mul_f32 v[34:35], v[34:35], v[38:39]
	v_cvt_f32_i32_e32 v30, v30
	v_pk_mul_f32 v[34:35], v[34:35], v[36:37]
	v_cvt_f32_i32_e32 v27, v27
	v_cvt_pk_bf16_f32 v45, v34, v35
	v_lshl_add_u64 v[34:35], v[52:53], 0, v[114:115]
	global_store_dwordx4 v[34:35], v[42:45], off sc1 nt
	ds_read_b32 v34, v181 offset:640
	v_cvt_f32_i32_e32 v26, v26
	v_add_u32_e32 v35, s17, v174
	v_cvt_f32_i32_e32 v33, v33
	v_cvt_f32_i32_e32 v32, v32
	s_waitcnt lgkmcnt(0)
	v_pk_mul_f32 v[38:39], v[160:161], v[34:35] op_sel_hi:[1,0]
	v_mul_f32_e32 v40, v34, v34
	v_pk_mul_f32 v[38:39], v[38:39], v[30:31]
	v_pk_mul_f32 v[26:27], v[30:31], v[26:27]
	v_pk_mul_f32 v[30:31], v[158:159], v[40:41] op_sel_hi:[1,0]
	v_cvt_f32_i32_e32 v29, v29
	v_pk_mul_f32 v[26:27], v[26:27], v[30:31]
	v_pk_mul_f32 v[30:31], v[156:157], v[34:35] op_sel_hi:[1,0]
	v_cvt_f32_i32_e32 v28, v28
	v_pk_mul_f32 v[30:31], v[30:31], v[32:33]
	v_exp_f32_e32 v38, v38
	v_exp_f32_e32 v30, v30
	v_exp_f32_e32 v31, v31
	v_exp_f32_e32 v39, v39
	v_cvt_f32_i32_e32 v23, v23
	v_cvt_f32_i32_e32 v22, v22
	v_pk_add_f32 v[30:31], v[30:31], 1.0 op_sel_hi:[1,0]
	v_pk_mul_f32 v[28:29], v[32:33], v[28:29]
	v_rcp_f32_e32 v30, v30
	v_rcp_f32_e32 v31, v31
	v_pk_mul_f32 v[32:33], v[154:155], v[40:41] op_sel_hi:[1,0]
	v_pk_add_f32 v[38:39], v[38:39], 1.0 op_sel_hi:[1,0]
	v_pk_mul_f32 v[28:29], v[28:29], v[32:33]
	v_rcp_f32_e32 v38, v38
	v_pk_mul_f32 v[28:29], v[28:29], v[30:31]
	v_pk_mul_f32 v[30:31], v[152:153], v[34:35] op_sel_hi:[1,0]
	v_rcp_f32_e32 v39, v39
	v_pk_mul_f32 v[30:31], v[30:31], v[22:23]
	v_cvt_f32_i32_e32 v19, v19
	v_exp_f32_e32 v30, v30
	v_exp_f32_e32 v31, v31
	v_cvt_f32_i32_e32 v18, v18
	v_cvt_f32_i32_e32 v25, v25
	v_cvt_f32_i32_e32 v24, v24
	v_pk_mul_f32 v[26:27], v[26:27], v[38:39]
	v_pk_mul_f32 v[18:19], v[22:23], v[18:19]
	v_cvt_pk_bf16_f32 v26, v26, v27
	v_cvt_pk_bf16_f32 v27, v28, v29
	v_pk_add_f32 v[28:29], v[30:31], 1.0 op_sel_hi:[1,0]
	v_pk_mul_f32 v[22:23], v[150:151], v[40:41] op_sel_hi:[1,0]
	v_rcp_f32_e32 v28, v28
	v_rcp_f32_e32 v29, v29
	v_pk_mul_f32 v[18:19], v[18:19], v[22:23]
	v_pk_mul_f32 v[22:23], v[148:149], v[34:35] op_sel_hi:[1,0]
	v_mad_i64_i32 v[36:37], s[26:27], v35, s46, v[162:163]
	v_pk_mul_f32 v[22:23], v[22:23], v[24:25]
	v_pk_mul_f32 v[18:19], v[18:19], v[28:29]
	v_exp_f32_e32 v22, v22
	v_exp_f32_e32 v23, v23
	v_cvt_pk_bf16_f32 v28, v18, v19
	v_cvt_f32_i32_e32 v19, v21
	v_cvt_f32_i32_e32 v18, v20
	v_pk_add_f32 v[20:21], v[22:23], 1.0 op_sel_hi:[1,0]
	v_pk_mul_f32 v[22:23], v[146:147], v[40:41] op_sel_hi:[1,0]
	v_rcp_f32_e32 v20, v20
	v_rcp_f32_e32 v21, v21
	v_pk_mul_f32 v[18:19], v[24:25], v[18:19]
	v_cvt_f32_i32_e32 v15, v15
	v_pk_mul_f32 v[18:19], v[18:19], v[22:23]
	v_cvt_f32_i32_e32 v14, v14
	v_pk_mul_f32 v[18:19], v[18:19], v[20:21]
	v_cvt_f32_i32_e32 v11, v11
	v_cvt_pk_bf16_f32 v29, v18, v19
	v_lshl_add_u64 v[18:19], v[36:37], 0, v[114:115]
	global_store_dwordx4 v[18:19], v[26:29], off sc1 nt
	ds_read_b32 v18, v181 offset:704
	v_cvt_f32_i32_e32 v10, v10
	v_add_u32_e32 v19, s17, v175
	v_cvt_f32_i32_e32 v17, v17
	v_cvt_f32_i32_e32 v16, v16
	s_waitcnt lgkmcnt(0)
	v_pk_mul_f32 v[22:23], v[160:161], v[18:19] op_sel_hi:[1,0]
	v_mul_f32_e32 v24, v18, v18
	v_pk_mul_f32 v[22:23], v[22:23], v[14:15]
	v_pk_mul_f32 v[10:11], v[14:15], v[10:11]
	v_pk_mul_f32 v[14:15], v[158:159], v[24:25] op_sel_hi:[1,0]
	v_cvt_f32_i32_e32 v13, v13
	v_pk_mul_f32 v[10:11], v[10:11], v[14:15]
	v_pk_mul_f32 v[14:15], v[156:157], v[18:19] op_sel_hi:[1,0]
	v_cvt_f32_i32_e32 v12, v12
	v_pk_mul_f32 v[14:15], v[14:15], v[16:17]
	v_exp_f32_e32 v22, v22
	v_exp_f32_e32 v14, v14
	v_exp_f32_e32 v15, v15
	v_exp_f32_e32 v23, v23
	v_cvt_f32_i32_e32 v7, v7
	v_cvt_f32_i32_e32 v6, v6
	v_pk_add_f32 v[14:15], v[14:15], 1.0 op_sel_hi:[1,0]
	v_pk_mul_f32 v[12:13], v[16:17], v[12:13]
	v_rcp_f32_e32 v14, v14
	v_rcp_f32_e32 v15, v15
	v_pk_mul_f32 v[16:17], v[154:155], v[24:25] op_sel_hi:[1,0]
	v_pk_add_f32 v[22:23], v[22:23], 1.0 op_sel_hi:[1,0]
	v_pk_mul_f32 v[12:13], v[12:13], v[16:17]
	v_rcp_f32_e32 v22, v22
	v_pk_mul_f32 v[12:13], v[12:13], v[14:15]
	v_pk_mul_f32 v[14:15], v[152:153], v[18:19] op_sel_hi:[1,0]
	v_rcp_f32_e32 v23, v23
	v_pk_mul_f32 v[14:15], v[14:15], v[6:7]
	v_cvt_f32_i32_e32 v3, v3
	v_exp_f32_e32 v14, v14
	v_exp_f32_e32 v15, v15
	v_cvt_f32_i32_e32 v2, v2
	v_cvt_f32_i32_e32 v9, v9
	v_cvt_f32_i32_e32 v8, v8
	v_pk_mul_f32 v[10:11], v[10:11], v[22:23]
	v_pk_mul_f32 v[2:3], v[6:7], v[2:3]
	v_cvt_pk_bf16_f32 v10, v10, v11
	v_cvt_pk_bf16_f32 v11, v12, v13
	v_pk_add_f32 v[12:13], v[14:15], 1.0 op_sel_hi:[1,0]
	v_pk_mul_f32 v[6:7], v[150:151], v[24:25] op_sel_hi:[1,0]
	v_rcp_f32_e32 v12, v12
	v_rcp_f32_e32 v13, v13
	v_pk_mul_f32 v[2:3], v[2:3], v[6:7]
	v_pk_mul_f32 v[6:7], v[148:149], v[18:19] op_sel_hi:[1,0]
	v_mad_i64_i32 v[20:21], s[26:27], v19, s46, v[162:163]
	v_pk_mul_f32 v[6:7], v[6:7], v[8:9]
	v_pk_mul_f32 v[2:3], v[2:3], v[12:13]
	v_exp_f32_e32 v6, v6
	v_exp_f32_e32 v7, v7
	v_cvt_pk_bf16_f32 v12, v2, v3
	v_cvt_f32_i32_e32 v3, v5
	v_cvt_f32_i32_e32 v2, v4
	v_pk_add_f32 v[4:5], v[6:7], 1.0 op_sel_hi:[1,0]
	v_pk_mul_f32 v[6:7], v[146:147], v[24:25] op_sel_hi:[1,0]
	v_rcp_f32_e32 v4, v4
	v_rcp_f32_e32 v5, v5
	v_pk_mul_f32 v[2:3], v[8:9], v[2:3]
	s_andn2_b64 vcc, exec, s[0:1]
	v_pk_mul_f32 v[2:3], v[2:3], v[6:7]
	s_mov_b64 s[0:1], -1
	v_pk_mul_f32 v[2:3], v[2:3], v[4:5]
	s_nop 0
	v_cvt_pk_bf16_f32 v13, v2, v3
	v_lshl_add_u64 v[2:3], v[20:21], 0, v[114:115]
	global_store_dwordx4 v[2:3], v[10:13], off sc1 nt
	s_cbranch_vccnz .LBB0_3383
	s_andn2_b64 vcc, exec, s[10:11]
	s_cbranch_vccnz .LBB0_3382
	s_barrier
	s_branch .LBB0_3382
